# all VALU trims combined: P6 direct row reduction, permlane-swap shuffles, folded min/max canonicalisation in A4 loop and P4 epilogue, 64-bit accumulator zeroing
# speedup vs baseline: 1.0051x; 1.0051x over previous
;     __device__ bool next(int i, Unit& u) const { const int j = i / 3, br = i - 3 * j; const int pmn = c + j * G; if (pmn >= 512) return false; u.pm = pmn >> 2; u.pn = br * 4 + (pmn & 3); return true; }
;     __device__ bool next(int i, Unit& u) const { const int j = i / 3, br = i - 3 * j; const int pmn = c + j * G; if (pmn >= 512) return false; u.pm = br * 128 + (pmn >> 2); u.pn = br * 4 + (pmn & 3); return true; }
; template <class Epi, class Sched, bool ALIGN_EPI = false, bool SP2 = false>
; __device__ __forceinline__ void gemm_phase(PG8_LAS unsigned char* lds, const Gemm g, const Sched& S, const Epi& E) {
;     ...
;         const bool has_next = S.next(ui + 1, nxt);
;         const char* nA = has_next ? (const char*)g.A + (size_t)nxt.pm * tstep : cA; const char* nB = has_next ? (const char*)g.Bt + (size_t)nxt.pn * tstep : cB;
;     ...
; #pragma unroll
;         for (int a = 0; a < 2; ++a)
; #pragma unroll
;             for (int b = 0; b < 2; ++b)
; #pragma unroll
;                 for (int m = 0; m < 4; ++m)
; #pragma unroll
;                     for (int n = 0; n < 2; ++n) acc[a][b][m][n] = (f32x4){0.f, 0.f, 0.f, 0.f};
.LBB0_165:
	s_ashr_i32 s15, s14, 31
	s_lshl_b64 s[16:17], s[14:15], 19
	s_add_u32 s16, s33, s16
	s_addc_u32 s17, s34, s17
	s_and_b64 s[18:19], s[8:9], exec
	s_cselect_b32 s11, s17, s25
	s_cselect_b32 s15, s16, s24
	s_ashr_i32 s13, s12, 31
	s_lshl_b64 s[18:19], s[12:13], 19
	s_add_u32 s18, s35, s18
	s_addc_u32 s19, s36, s19
	s_and_b64 s[26:27], s[8:9], exec
	s_cselect_b32 s13, s19, s23
	s_cselect_b32 s21, s18, s22
	s_add_u32 s56, s22, 0x100
	s_addc_u32 s57, s23, 0
	s_add_u32 s22, s24, 0x40080
	v_mov_b64_e32 v[2:3], 0
	v_mov_b64_e32 v[4:5], 0
	v_mov_b64_e32 v[6:7], 0
	v_mov_b64_e32 v[8:9], 0
	v_mov_b64_e32 v[10:11], 0
	v_mov_b64_e32 v[12:13], 0
	v_mov_b64_e32 v[14:15], 0
	v_mov_b64_e32 v[16:17], 0
	v_mov_b64_e32 v[18:19], 0
	v_mov_b64_e32 v[20:21], 0
	v_mov_b64_e32 v[22:23], 0
	v_mov_b64_e32 v[24:25], 0
	v_mov_b64_e32 v[26:27], 0
	v_mov_b64_e32 v[28:29], 0
	v_mov_b64_e32 v[30:31], 0
	v_mov_b64_e32 v[32:33], 0
	v_mov_b64_e32 v[34:35], 0
	v_mov_b64_e32 v[36:37], 0
	v_mov_b64_e32 v[38:39], 0
	v_mov_b64_e32 v[40:41], 0
	v_mov_b64_e32 v[42:43], 0
	v_mov_b64_e32 v[44:45], 0
	v_mov_b64_e32 v[46:47], 0
	v_mov_b64_e32 v[48:49], 0
	v_mov_b64_e32 v[50:51], 0
	v_mov_b64_e32 v[52:53], 0
	v_mov_b64_e32 v[54:55], 0
	v_mov_b64_e32 v[56:57], 0
	v_mov_b64_e32 v[58:59], 0
	v_mov_b64_e32 v[60:61], 0
	v_mov_b64_e32 v[62:63], 0
	v_mov_b64_e32 v[64:65], 0
	v_mov_b64_e32 v[66:67], 0
	v_mov_b64_e32 v[68:69], 0
	v_mov_b64_e32 v[70:71], 0
	v_mov_b64_e32 v[72:73], 0
	v_mov_b64_e32 v[74:75], 0
	v_mov_b64_e32 v[76:77], 0
	v_mov_b64_e32 v[78:79], 0
	v_mov_b64_e32 v[80:81], 0
	v_mov_b64_e32 v[82:83], 0
	v_mov_b64_e32 v[84:85], 0
	v_mov_b64_e32 v[86:87], 0
	v_mov_b64_e32 v[88:89], 0
	v_mov_b64_e32 v[90:91], 0
	v_mov_b64_e32 v[92:93], 0
	v_mov_b64_e32 v[94:95], 0
	v_mov_b64_e32 v[96:97], 0
	v_mov_b64_e32 v[98:99], 0
	v_mov_b64_e32 v[100:101], 0
	v_mov_b64_e32 v[102:103], 0
	v_mov_b64_e32 v[104:105], 0
	v_mov_b64_e32 v[106:107], 0
	v_mov_b64_e32 v[108:109], 0
	v_mov_b64_e32 v[110:111], 0
	v_mov_b64_e32 v[112:113], 0
	v_mov_b64_e32 v[114:115], 0
	v_mov_b64_e32 v[116:117], 0
	v_mov_b64_e32 v[118:119], 0
	v_mov_b64_e32 v[120:121], 0
	v_mov_b64_e32 v[122:123], 0
	v_mov_b64_e32 v[124:125], 0
	v_mov_b64_e32 v[126:127], 0
	v_mov_b64_e32 v[128:129], 0
	s_addc_u32 s23, s25, 0
	s_mov_b32 s58, -2
	s_mov_b64 vcc, 0x80

; __device__ __forceinline__ void unit_a4(const AttnArgs& A, int b, int hg, int c, LAS unsigned char* lds) {
;     ...
;             f32x16 p0, p1; qkt(p0, p1, lds + st * 65536 + hh * 8192, qr, r32, hi);
;     ...
;                 for (int i4 = 0; i4 < 4; ++i4) { float rr[4];
; #pragma unroll
;                     for (int j = 0; j < 4; ++j) { const float z = p ? p1[4 * i4 + j] : p0[4 * i4 + j]; float rv = __builtin_amdgcn_rcpf(1.0f + __builtin_amdgcn_exp2f(fminf(z, 80.f)));
;                         if (diag) { const int kk = 32 * p + 8 * i4 + 4 * hi + j; if (kk >= qd) rv = 1.0f; }
;                         rr[j] = rv; }
;                     const float sc = rr[3], sb = rr[3] * rr[2], sa = sb * rr[1], R = sa * rr[0];
;                     const float w0 = (1.0f - rr[0]) * sa, w1 = (1.0f - rr[1]) * sb, w2 = (1.0f - rr[2]) * sc, w3 = (1.0f - rr[3]);
;                     if (p) { p1[4 * i4] = w0; p1[4 * i4 + 1] = w1; p1[4 * i4 + 2] = w2; p1[4 * i4 + 3] = w3; } else { p0[4 * i4] = w0; p0[4 * i4 + 1] = w1; p0[4 * i4 + 2] = w2; p0[4 * i4 + 3] = w3; }
;                     const float Ro = __shfl_xor(R, 32);
;                     G[2 * (4 * p + i4)] = hi ? Ro : R; G[2 * (4 * p + i4) + 1] = hi ? R : Ro; }
.LBB0_367:
	s_and_b32 s95, s76, 1
	v_cmp_neq_f32_e32 vcc, 0, v140
	s_cbranch_vccz .LBB0_369
	s_lshl_b32 s1, s95, 16
	s_add_i32 s94, s0, s1
	v_add3_u32 v0, s94, v138, v139
	ds_read_b128 v[2:5], v0
	ds_read_b128 v[6:9], v0 offset:512
	ds_read_b128 v[10:13], v0 offset:2048
	ds_read_b128 v[142:145], v0 offset:2560
	ds_read_b128 v[146:149], v0 offset:4096
	ds_read_b128 v[150:153], v0 offset:4608
	ds_read_b128 v[154:157], v0 offset:6144
	ds_read_b128 v[158:161], v0 offset:6656
	s_waitcnt lgkmcnt(7)
	v_mfma_f32_32x32x16_bf16 v[64:79], v[2:5], v[104:107], 0
	s_waitcnt lgkmcnt(6)
	v_mfma_f32_32x32x16_bf16 v[48:63], v[6:9], v[104:107], 0
	s_waitcnt lgkmcnt(5)
	v_mfma_f32_32x32x16_bf16 v[64:79], v[10:13], v[116:119], v[64:79]
	s_waitcnt lgkmcnt(4)
	v_mfma_f32_32x32x16_bf16 v[48:63], v[142:145], v[116:119], v[48:63]
	s_waitcnt lgkmcnt(3)
	v_mfma_f32_32x32x16_bf16 v[64:79], v[146:149], v[120:123], v[64:79]
	s_waitcnt lgkmcnt(2)
	v_mfma_f32_32x32x16_bf16 v[48:63], v[150:153], v[120:123], v[48:63]
	s_waitcnt lgkmcnt(1)
	v_mfma_f32_32x32x16_bf16 v[64:79], v[154:157], v[124:127], v[64:79]
	s_waitcnt lgkmcnt(0)
	v_mfma_f32_32x32x16_bf16 v[48:63], v[158:161], v[124:127], v[48:63]
	s_nop 9
	v_min_f32_e32 v3, 0x42a00000, v64
	v_exp_f32_e32 v3, v3
	v_and_b32_e32 v2, 64, v240
	v_xor_b32_e32 v0, 32, v240
	v_add_u32_e32 v2, 64, v2
	v_cmp_lt_i32_e32 vcc, v0, v2
	v_add_f32_e32 v2, 1.0, v3
	v_rcp_f32_e32 v2, v2
	v_min_f32_e32 v3, 0x42a00000, v65
	v_exp_f32_e32 v3, v3
	s_cmp_eq_u32 s76, 0
	v_cndmask_b32_e32 v0, v240, v0, vcc
	v_cndmask_b32_e64 v4, 1.0, v2, s[10:11]
	s_cselect_b64 vcc, -1, 0
	v_cndmask_b32_e32 v4, v2, v4, vcc
	v_add_f32_e32 v2, 1.0, v3
	v_min_f32_e32 v3, 0x42a00000, v66
	v_exp_f32_e32 v3, v3
	v_min_f32_e32 v5, 0x42a00000, v67
	v_exp_f32_e32 v5, v5
	v_rcp_f32_e32 v2, v2
	v_add_f32_e32 v3, 1.0, v3
	v_rcp_f32_e32 v3, v3
	v_add_f32_e32 v5, 1.0, v5
	v_rcp_f32_e32 v5, v5
	v_cndmask_b32_e64 v6, 1.0, v2, s[12:13]
	v_cndmask_b32_e32 v6, v2, v6, vcc
	v_cndmask_b32_e64 v2, 1.0, v3, s[14:15]
	v_cndmask_b32_e32 v2, v3, v2, vcc
	v_cndmask_b32_e64 v3, 1.0, v5, s[16:17]
	v_cndmask_b32_e32 v5, v5, v3, vcc
	v_mul_f32_e32 v7, v5, v2
	v_sub_f32_e32 v2, 1.0, v2
	v_mul_f32_e32 v8, v6, v7
	v_sub_f32_e32 v3, 1.0, v5
	v_mul_f32_e32 v2, v5, v2
	v_sub_f32_e32 v5, 1.0, v6
	v_min_f32_e32 v6, 0x42a00000, v68
	v_exp_f32_e32 v6, v6
	v_lshlrev_b32_e32 v0, 2, v0
	v_mul_f32_e32 v9, v4, v8
	v_sub_f32_e32 v4, 1.0, v4
	v_mul_f32_e32 v64, v7, v5
	ds_bpermute_b32 v5, v0, v9
	v_mul_f32_e32 v65, v4, v8
	v_add_f32_e32 v4, 1.0, v6
	v_rcp_f32_e32 v4, v4
	v_min_f32_e32 v6, 0x42a00000, v69
	v_exp_f32_e32 v6, v6
	s_waitcnt lgkmcnt(0)
	v_cndmask_b32_e64 v66, v5, v9, s[6:7]
	v_cndmask_b32_e64 v67, v9, v5, s[6:7]
	v_cndmask_b32_e64 v5, 1.0, v4, s[18:19]
	v_cndmask_b32_e32 v7, v4, v5, vcc
	v_add_f32_e32 v4, 1.0, v6
	v_min_f32_e32 v5, 0x42a00000, v70
	v_exp_f32_e32 v5, v5
	v_min_f32_e32 v6, 0x42a00000, v71
	v_exp_f32_e32 v6, v6
	v_rcp_f32_e32 v4, v4
	v_add_f32_e32 v5, 1.0, v5
	v_rcp_f32_e32 v5, v5
	v_add_f32_e32 v6, 1.0, v6
	v_rcp_f32_e32 v6, v6
	v_cndmask_b32_e64 v8, 1.0, v4, s[20:21]
	v_cndmask_b32_e32 v8, v4, v8, vcc
	v_cndmask_b32_e64 v4, 1.0, v5, s[22:23]
	v_cndmask_b32_e32 v4, v5, v4, vcc
	v_cndmask_b32_e64 v5, 1.0, v6, s[24:25]
	v_cndmask_b32_e32 v6, v6, v5, vcc
	v_mul_f32_e32 v9, v6, v4
	v_sub_f32_e32 v4, 1.0, v4
	v_mul_f32_e32 v10, v8, v9
	v_sub_f32_e32 v5, 1.0, v6
	v_mul_f32_e32 v4, v6, v4
	v_sub_f32_e32 v6, 1.0, v8
	v_min_f32_e32 v8, 0x42a00000, v72
	v_exp_f32_e32 v8, v8
	v_mul_f32_e32 v11, v7, v10
	v_sub_f32_e32 v7, 1.0, v7
	v_mul_f32_e32 v68, v9, v6
	ds_bpermute_b32 v6, v0, v11
	v_mul_f32_e32 v69, v7, v10
	v_add_f32_e32 v7, 1.0, v8
	v_rcp_f32_e32 v7, v7
	v_min_f32_e32 v8, 0x42a00000, v73
	v_exp_f32_e32 v8, v8
	s_waitcnt lgkmcnt(0)
	v_cndmask_b32_e64 v70, v6, v11, s[6:7]
	v_cndmask_b32_e64 v71, v11, v6, s[6:7]
	v_cndmask_b32_e64 v6, 1.0, v7, s[26:27]
	v_cndmask_b32_e32 v9, v7, v6, vcc
	v_add_f32_e32 v6, 1.0, v8
	v_min_f32_e32 v7, 0x42a00000, v74
	v_exp_f32_e32 v7, v7
	v_min_f32_e32 v8, 0x42a00000, v75
	v_exp_f32_e32 v8, v8
	v_rcp_f32_e32 v6, v6
	v_add_f32_e32 v7, 1.0, v7
	v_rcp_f32_e32 v7, v7
	v_add_f32_e32 v8, 1.0, v8
	v_rcp_f32_e32 v8, v8
	v_cndmask_b32_e64 v10, 1.0, v6, s[28:29]
	v_cndmask_b32_e32 v10, v6, v10, vcc
	v_cndmask_b32_e64 v6, 1.0, v7, s[30:31]
	v_cndmask_b32_e32 v6, v7, v6, vcc
	v_cndmask_b32_e64 v7, 1.0, v8, s[34:35]
	v_cndmask_b32_e32 v8, v8, v7, vcc
	v_mul_f32_e32 v11, v8, v6
	v_sub_f32_e32 v6, 1.0, v6
	v_mul_f32_e32 v12, v10, v11
	v_sub_f32_e32 v7, 1.0, v8
	v_mul_f32_e32 v6, v8, v6
	v_sub_f32_e32 v8, 1.0, v10
	v_min_f32_e32 v10, 0x42a00000, v76
	v_exp_f32_e32 v10, v10
	v_mul_f32_e32 v13, v9, v12
	v_sub_f32_e32 v9, 1.0, v9
	v_mul_f32_e32 v72, v11, v8
	ds_bpermute_b32 v8, v0, v13
	v_mul_f32_e32 v73, v9, v12
	v_add_f32_e32 v9, 1.0, v10
	v_rcp_f32_e32 v9, v9
	v_min_f32_e32 v10, 0x42a00000, v77
	v_exp_f32_e32 v10, v10
	s_waitcnt lgkmcnt(0)
	v_cndmask_b32_e64 v74, v8, v13, s[6:7]
	v_cndmask_b32_e64 v75, v13, v8, s[6:7]
	v_cndmask_b32_e64 v8, 1.0, v9, s[36:37]
	v_cndmask_b32_e32 v11, v9, v8, vcc
	v_add_f32_e32 v8, 1.0, v10
	v_min_f32_e32 v9, 0x42a00000, v78
	v_exp_f32_e32 v9, v9
	v_min_f32_e32 v10, 0x42a00000, v79
	v_exp_f32_e32 v10, v10
	v_rcp_f32_e32 v8, v8
	v_add_f32_e32 v9, 1.0, v9
	v_rcp_f32_e32 v9, v9
	v_add_f32_e32 v10, 1.0, v10
	v_rcp_f32_e32 v10, v10
	v_cndmask_b32_e64 v12, 1.0, v8, s[38:39]
	v_cndmask_b32_e32 v12, v8, v12, vcc
	v_cndmask_b32_e64 v8, 1.0, v9, s[40:41]
	v_cndmask_b32_e32 v8, v9, v8, vcc
	v_cndmask_b32_e64 v9, 1.0, v10, s[42:43]
	v_cndmask_b32_e32 v10, v10, v9, vcc
	v_mul_f32_e32 v13, v10, v8
	v_sub_f32_e32 v8, 1.0, v8
	v_mul_f32_e32 v14, v12, v13
	v_sub_f32_e32 v9, 1.0, v10
	v_mul_f32_e32 v8, v10, v8
	v_sub_f32_e32 v10, 1.0, v12
	v_min_f32_e32 v12, 0x42a00000, v48
	v_exp_f32_e32 v12, v12
	v_mul_f32_e32 v15, v11, v14
	v_sub_f32_e32 v11, 1.0, v11
	v_mul_f32_e32 v76, v13, v10
	ds_bpermute_b32 v10, v0, v15
	v_mul_f32_e32 v77, v11, v14
	v_add_f32_e32 v11, 1.0, v12
	v_rcp_f32_e32 v11, v11
	v_min_f32_e32 v12, 0x42a00000, v49
	v_exp_f32_e32 v12, v12
	s_waitcnt lgkmcnt(0)
; __device__ __forceinline__ void unit_a4(const AttnArgs& A, int b, int hg, int c, LAS unsigned char* lds) {
;     ...
;                 for (int i4 = 0; i4 < 4; ++i4) { float rr[4];
; #pragma unroll
;                     for (int j = 0; j < 4; ++j) { const float z = p ? p1[4 * i4 + j] : p0[4 * i4 + j]; float rv = __builtin_amdgcn_rcpf(1.0f + __builtin_amdgcn_exp2f(fminf(z, 80.f)));
;                         if (diag) { const int kk = 32 * p + 8 * i4 + 4 * hi + j; if (kk >= qd) rv = 1.0f; }
;                         rr[j] = rv; }
;                     const float sc = rr[3], sb = rr[3] * rr[2], sa = sb * rr[1], R = sa * rr[0];
;                     const float w0 = (1.0f - rr[0]) * sa, w1 = (1.0f - rr[1]) * sb, w2 = (1.0f - rr[2]) * sc, w3 = (1.0f - rr[3]);
;                     if (p) { p1[4 * i4] = w0; p1[4 * i4 + 1] = w1; p1[4 * i4 + 2] = w2; p1[4 * i4 + 3] = w3; } else { p0[4 * i4] = w0; p0[4 * i4 + 1] = w1; p0[4 * i4 + 2] = w2; p0[4 * i4 + 3] = w3; }
;                     const float Ro = __shfl_xor(R, 32);
;                     G[2 * (4 * p + i4)] = hi ? Ro : R; G[2 * (4 * p + i4) + 1] = hi ? R : Ro; }
	v_cndmask_b32_e64 v78, v10, v15, s[6:7]
	v_cndmask_b32_e64 v79, v15, v10, s[6:7]
	v_cndmask_b32_e64 v10, 1.0, v11, s[44:45]
	v_cndmask_b32_e32 v13, v11, v10, vcc
	v_add_f32_e32 v10, 1.0, v12
	v_min_f32_e32 v11, 0x42a00000, v50
	v_exp_f32_e32 v11, v11
	v_min_f32_e32 v12, 0x42a00000, v51
	v_exp_f32_e32 v12, v12
	v_rcp_f32_e32 v10, v10
	v_add_f32_e32 v11, 1.0, v11
	v_rcp_f32_e32 v11, v11
	v_add_f32_e32 v12, 1.0, v12
	v_rcp_f32_e32 v12, v12
	v_cndmask_b32_e64 v14, 1.0, v10, s[46:47]
	v_cndmask_b32_e32 v14, v10, v14, vcc
	v_cndmask_b32_e64 v10, 1.0, v11, s[48:49]
	v_cndmask_b32_e32 v10, v11, v10, vcc
	v_cndmask_b32_e64 v11, 1.0, v12, s[50:51]
	v_cndmask_b32_e32 v12, v12, v11, vcc
	v_mul_f32_e32 v15, v12, v10
	v_sub_f32_e32 v10, 1.0, v10
	v_mul_f32_e32 v48, v14, v15
	v_sub_f32_e32 v11, 1.0, v12
	v_mul_f32_e32 v10, v12, v10
	v_sub_f32_e32 v12, 1.0, v14
	v_min_f32_e32 v14, 0x42a00000, v52
	v_exp_f32_e32 v14, v14
	v_mul_f32_e32 v49, v13, v48
	v_sub_f32_e32 v13, 1.0, v13
	v_mul_f32_e32 v141, v15, v12
	ds_bpermute_b32 v12, v0, v49
	v_mul_f32_e32 v142, v13, v48
	v_add_f32_e32 v13, 1.0, v14
	v_rcp_f32_e32 v13, v13
	v_min_f32_e32 v14, 0x42a00000, v53
	v_exp_f32_e32 v14, v14
	s_waitcnt lgkmcnt(0)
	v_cndmask_b32_e64 v50, v12, v49, s[6:7]
	v_cndmask_b32_e64 v51, v49, v12, s[6:7]
	v_cndmask_b32_e64 v12, 1.0, v13, s[52:53]
	v_cndmask_b32_e32 v15, v13, v12, vcc
	v_add_f32_e32 v12, 1.0, v14
	v_min_f32_e32 v13, 0x42a00000, v54
	v_exp_f32_e32 v13, v13
	v_min_f32_e32 v14, 0x42a00000, v55
	v_exp_f32_e32 v14, v14
	v_rcp_f32_e32 v12, v12
	v_add_f32_e32 v13, 1.0, v13
	v_rcp_f32_e32 v13, v13
	v_add_f32_e32 v14, 1.0, v14
	v_rcp_f32_e32 v14, v14
	v_cndmask_b32_e64 v48, 1.0, v12, s[54:55]
	v_cndmask_b32_e32 v48, v12, v48, vcc
	v_cndmask_b32_e64 v12, 1.0, v13, s[56:57]
	v_cndmask_b32_e32 v12, v13, v12, vcc
	v_cndmask_b32_e64 v13, 1.0, v14, s[58:59]
	v_cndmask_b32_e32 v14, v14, v13, vcc
	v_mul_f32_e32 v49, v14, v12
	v_sub_f32_e32 v12, 1.0, v12
	v_mul_f32_e32 v52, v48, v49
	v_sub_f32_e32 v13, 1.0, v14
	v_mul_f32_e32 v12, v14, v12
	v_sub_f32_e32 v14, 1.0, v48
	v_min_f32_e32 v48, 0x42a00000, v56
	v_exp_f32_e32 v48, v48
	v_mul_f32_e32 v53, v15, v52
	v_sub_f32_e32 v15, 1.0, v15
	v_mul_f32_e32 v143, v49, v14
	ds_bpermute_b32 v14, v0, v53
	v_mul_f32_e32 v144, v15, v52
	v_add_f32_e32 v15, 1.0, v48
	v_rcp_f32_e32 v15, v15
	v_min_f32_e32 v48, 0x42a00000, v57
	v_exp_f32_e32 v48, v48
	s_waitcnt lgkmcnt(0)
	v_cndmask_b32_e64 v52, v14, v53, s[6:7]
	v_cndmask_b32_e64 v53, v53, v14, s[6:7]
	v_cndmask_b32_e64 v14, 1.0, v15, s[60:61]
	v_cndmask_b32_e32 v49, v15, v14, vcc
	v_add_f32_e32 v14, 1.0, v48
	v_min_f32_e32 v15, 0x42a00000, v58
	v_exp_f32_e32 v15, v15
	v_min_f32_e32 v48, 0x42a00000, v59
	v_exp_f32_e32 v48, v48
	v_rcp_f32_e32 v14, v14
	v_add_f32_e32 v15, 1.0, v15
	v_rcp_f32_e32 v15, v15
	v_add_f32_e32 v48, 1.0, v48
	v_rcp_f32_e32 v48, v48
	v_cndmask_b32_e64 v54, 1.0, v14, s[62:63]
	v_cndmask_b32_e32 v54, v14, v54, vcc
	v_cndmask_b32_e64 v14, 1.0, v15, s[64:65]
	v_cndmask_b32_e32 v14, v15, v14, vcc
	v_cndmask_b32_e64 v15, 1.0, v48, s[66:67]
	v_cndmask_b32_e32 v48, v48, v15, vcc
	v_mul_f32_e32 v55, v48, v14
	v_sub_f32_e32 v14, 1.0, v14
	v_mul_f32_e32 v56, v54, v55
	v_sub_f32_e32 v15, 1.0, v48
	v_mul_f32_e32 v14, v48, v14
	v_sub_f32_e32 v48, 1.0, v54
	v_min_f32_e32 v54, 0x42a00000, v60
	v_exp_f32_e32 v54, v54
	v_mul_f32_e32 v57, v49, v56
	v_sub_f32_e32 v49, 1.0, v49
	v_mul_f32_e32 v145, v55, v48
	ds_bpermute_b32 v48, v0, v57
	v_mul_f32_e32 v146, v49, v56
	v_add_f32_e32 v49, 1.0, v54
	v_rcp_f32_e32 v49, v49
	v_min_f32_e32 v54, 0x42a00000, v61
	v_exp_f32_e32 v54, v54
	s_waitcnt lgkmcnt(0)
	v_cndmask_b32_e64 v55, v48, v57, s[6:7]
	v_cndmask_b32_e64 v56, v57, v48, s[6:7]
	v_cndmask_b32_e64 v48, 1.0, v49, s[68:69]
	v_cndmask_b32_e32 v57, v49, v48, vcc
	v_add_f32_e32 v48, 1.0, v54
	v_min_f32_e32 v49, 0x42a00000, v62
	v_exp_f32_e32 v49, v49
	v_min_f32_e32 v54, 0x42a00000, v63
	v_exp_f32_e32 v54, v54
	v_rcp_f32_e32 v48, v48
	v_add_f32_e32 v49, 1.0, v49
	v_rcp_f32_e32 v49, v49
	v_add_f32_e32 v54, 1.0, v54
	v_rcp_f32_e32 v54, v54
	v_cndmask_b32_e64 v58, 1.0, v48, s[70:71]
	v_cndmask_b32_e32 v58, v48, v58, vcc
	v_cndmask_b32_e64 v48, 1.0, v49, s[72:73]
	v_cndmask_b32_e32 v48, v49, v48, vcc
	v_cndmask_b32_e64 v49, 1.0, v54, s[74:75]
	v_cndmask_b32_e32 v54, v54, v49, vcc
	v_mul_f32_e32 v59, v54, v48
	v_mul_f32_e32 v60, v58, v59
	v_mul_f32_e32 v61, v57, v60
	ds_bpermute_b32 v0, v0, v61
	v_sub_f32_e32 v48, 1.0, v48
	v_sub_f32_e32 v49, 1.0, v54
	v_mul_f32_e32 v48, v54, v48
	v_sub_f32_e32 v54, 1.0, v58
	v_mul_f32_e32 v62, v59, v54
	v_sub_f32_e32 v54, 1.0, v57
	v_mul_f32_e32 v63, v54, v60
	s_waitcnt lgkmcnt(0)
; #define LAS __attribute__((address_space(3)))
; #define MFMA32(a, b, c) __builtin_amdgcn_mfma_f32_32x32x16_bf16((a), (b), (c), 0, 0, 0)
; __device__ __forceinline__ s16x4 vtr(const LAS unsigned char* p) { return __builtin_bit_cast(s16x4, __builtin_amdgcn_ds_read_tr16_b64_v4i16((LAS v4i16_t*)p)); }
; __device__ __forceinline__ bf16x8 pack8(const f32x16& p, int s) { u32x4 w; w.x = cvt_pk_bf16(p[8 * s], p[8 * s + 1]); w.y = cvt_pk_bf16(p[8 * s + 2], p[8 * s + 3]); w.z = cvt_pk_bf16(p[8 * s + 4], p[8 * s + 5]); w.w = cvt_pk_bf16(p[8 * s + 6], p[8 * s + 7]); return __builtin_bit_cast(bf16x8, w); }
; #define LAS __attribute__((address_space(3)))
; template <int NB> __device__ __forceinline__ void pv(f32x16* o, const LAS unsigned char* vimg, int vl, const f32x16& p0, const f32x16& p1) {
;     const bf16x8 pf[4] = {pack8(p0, 0), pack8(p0, 1), pack8(p1, 0), pack8(p1, 1)};
;     s16x4 lo[2][4], hh[2][4];
; #pragma unroll
;     for (int ks = 0; ks < 4; ++ks) { const LAS unsigned char* vp = vimg + vl + ks * 1024; lo[0][ks] = vtr(vp); hh[0][ks] = vtr(vp + 512); }
; #pragma unroll
;     for (int blk = 0; blk < NB; ++blk) {
;         if (blk + 1 < NB) {
; #pragma unroll
;             for (int ks = 0; ks < 4; ++ks) { const LAS unsigned char* vp = vimg + vl + (blk + 1) * 4096 + ks * 1024; lo[(blk + 1) & 1][ks] = vtr(vp); hh[(blk + 1) & 1][ks] = vtr(vp + 512); } }
;         __builtin_amdgcn_sched_barrier(0);
; #pragma unroll
;         for (int ks = 0; ks < 4; ++ks) { const s16x4 a = lo[blk & 1][ks], b = hh[blk & 1][ks];
;             const bf16x8 vf = (bf16x8){a[0], a[1], a[2], a[3], b[0], b[1], b[2], b[3]};
;             o[blk] = MFMA32(vf, pf[ks], o[blk]); }
;         __builtin_amdgcn_sched_barrier(0);
;     }
; __device__ __forceinline__ void unit_a4(const AttnArgs& A, int b, int hg, int c, LAS unsigned char* lds) {
;     ...
;             float Ee[8], Eo[8]; Eo[7] = pc;
; #pragma unroll
;             for (int q = 7; q >= 0; --q) { Ee[q] = Eo[q] * G[2 * q + 1]; if (q > 0) Eo[q - 1] = Ee[q] * G[2 * q]; }
;             pc = Ee[0] * G[0];
; #pragma unroll
;             for (int q = 0; q < 8; ++q) { const float e = hi ? Eo[q] : Ee[q];
; #pragma unroll
;                 for (int j = 0; j < 4; ++j) { if (q < 4) p0[4 * q + j] *= e; else p1[4 * (q - 4) + j] *= e; } }
;             pv<2>(o, lds + st * 65536 + 32768 + hh * 8192, vl, p0, p1);
	v_cndmask_b32_e64 v54, v61, v0, s[6:7]
	v_mul_f32_e32 v147, v140, v54
	v_cndmask_b32_e64 v0, v0, v61, s[6:7]
	v_mul_f32_e32 v148, v0, v147
	v_mul_f32_e32 v149, v56, v148
	v_mul_f32_e32 v60, v55, v149
	v_mul_f32_e32 v61, v53, v60
	v_mul_f32_e32 v58, v52, v61
	v_mul_f32_e32 v59, v51, v58
	v_mul_f32_e32 v56, v50, v59
	v_mul_f32_e32 v57, v79, v56
	v_mul_f32_e32 v54, v78, v57
	v_mul_f32_e32 v55, v75, v54
	v_mul_f32_e32 v52, v74, v55
	v_mul_f32_e32 v53, v71, v52
	v_mul_f32_e32 v0, v70, v53
	v_mul_f32_e32 v67, v67, v0
	v_cndmask_b32_e64 v0, v0, v67, s[6:7]
	v_mul_f32_e32 v65, v65, v0
	v_mul_f32_e32 v64, v64, v0
	v_pk_mul_f32 v[50:51], v[2:3], v[0:1] op_sel_hi:[1,0]
	v_cndmask_b32_e64 v0, v52, v53, s[6:7]
	v_mul_f32_e32 v69, v69, v0
	v_mul_f32_e32 v68, v68, v0
	v_pk_mul_f32 v[52:53], v[4:5], v[0:1] op_sel_hi:[1,0]
	v_cndmask_b32_e64 v0, v54, v55, s[6:7]
	v_mul_f32_e32 v70, v73, v0
	v_mul_f32_e32 v71, v72, v0
	v_pk_mul_f32 v[54:55], v[6:7], v[0:1] op_sel_hi:[1,0]
	v_cndmask_b32_e64 v0, v56, v57, s[6:7]
	v_mul_f32_e32 v72, v77, v0
	v_mul_f32_e32 v73, v76, v0
	v_pk_mul_f32 v[56:57], v[8:9], v[0:1] op_sel_hi:[1,0]
	v_cndmask_b32_e64 v0, v58, v59, s[6:7]
	v_mul_f32_e32 v74, v142, v0
	v_mul_f32_e32 v75, v141, v0
	v_pk_mul_f32 v[58:59], v[10:11], v[0:1] op_sel_hi:[1,0]
	v_cndmask_b32_e64 v0, v60, v61, s[6:7]
	v_mul_f32_e32 v76, v144, v0
	v_mul_f32_e32 v77, v143, v0
	v_pk_mul_f32 v[60:61], v[12:13], v[0:1] op_sel_hi:[1,0]
	v_cndmask_b32_e64 v0, v148, v149, s[6:7]
	v_mul_f32_e32 v141, v146, v0
	v_mul_f32_e32 v142, v145, v0
	v_pk_mul_f32 v[14:15], v[14:15], v[0:1] op_sel_hi:[1,0]
	v_cndmask_b32_e64 v0, v140, v147, s[6:7]
	v_mul_f32_e32 v144, v63, v0
	v_mul_f32_e32 v145, v62, v0
	v_pk_mul_f32 v[146:147], v[48:49], v[0:1] op_sel_hi:[1,0]
	v_add_u32_e32 v0, s94, v135
	v_add3_u32 v0, v0, v137, v129
	v_mul_f32_e32 v140, v66, v67
	v_cvt_pk_bf16_f32 v2, v65, v64
	v_cvt_pk_bf16_f32 v3, v50, v51
	v_cvt_pk_bf16_f32 v4, v69, v68
	v_cvt_pk_bf16_f32 v5, v52, v53
	v_cvt_pk_bf16_f32 v6, v70, v71
	v_cvt_pk_bf16_f32 v7, v54, v55
	v_cvt_pk_bf16_f32 v8, v72, v73
	v_cvt_pk_bf16_f32 v9, v56, v57
	v_cvt_pk_bf16_f32 v10, v74, v75
	v_cvt_pk_bf16_f32 v11, v58, v59
	v_cvt_pk_bf16_f32 v12, v76, v77
	v_cvt_pk_bf16_f32 v13, v60, v61
	ds_read_b64_tr_b16 v[48:49], v0 offset:32768
	ds_read_b64_tr_b16 v[50:51], v0 offset:33280
	ds_read_b64_tr_b16 v[52:53], v0 offset:33792
	ds_read_b64_tr_b16 v[54:55], v0 offset:34304
	ds_read_b64_tr_b16 v[56:57], v0 offset:34816
	ds_read_b64_tr_b16 v[58:59], v0 offset:35328
	ds_read_b64_tr_b16 v[60:61], v0 offset:35840
	ds_read_b64_tr_b16 v[62:63], v0 offset:36352
	ds_read_b64_tr_b16 v[64:65], v0 offset:36864
	ds_read_b64_tr_b16 v[66:67], v0 offset:37376
	ds_read_b64_tr_b16 v[68:69], v0 offset:37888
	ds_read_b64_tr_b16 v[70:71], v0 offset:38400
	ds_read_b64_tr_b16 v[72:73], v0 offset:38912
	ds_read_b64_tr_b16 v[74:75], v0 offset:39424
	ds_read_b64_tr_b16 v[76:77], v0 offset:39936
	ds_read_b64_tr_b16 v[78:79], v0 offset:40448
	v_cvt_pk_bf16_f32 v142, v141, v142
	v_cvt_pk_bf16_f32 v143, v14, v15
	v_cvt_pk_bf16_f32 v144, v144, v145
	v_cvt_pk_bf16_f32 v145, v146, v147
	s_waitcnt lgkmcnt(14)
	v_mfma_f32_32x32x16_bf16 v[32:47], v[48:51], v[2:5], v[32:47]
	s_waitcnt lgkmcnt(12)
	v_mfma_f32_32x32x16_bf16 v[32:47], v[52:55], v[6:9], v[32:47]
	s_waitcnt lgkmcnt(10)
	v_mfma_f32_32x32x16_bf16 v[32:47], v[56:59], v[10:13], v[32:47]
	s_waitcnt lgkmcnt(8)
	v_mfma_f32_32x32x16_bf16 v[32:47], v[60:63], v[142:145], v[32:47]
	s_waitcnt lgkmcnt(6)
	v_mfma_f32_32x32x16_bf16 v[16:31], v[64:67], v[2:5], v[16:31]
	s_waitcnt lgkmcnt(4)
	v_mfma_f32_32x32x16_bf16 v[16:31], v[68:71], v[6:9], v[16:31]
	s_waitcnt lgkmcnt(2)
	v_mfma_f32_32x32x16_bf16 v[16:31], v[72:75], v[10:13], v[16:31]
	s_waitcnt lgkmcnt(0)
	v_mfma_f32_32x32x16_bf16 v[16:31], v[76:79], v[142:145], v[16:31]

; #define GAS __attribute__((address_space(1)))
; __device__ __forceinline__ float bf_lo(unsigned u) { return __uint_as_float(u << 16); }
; __device__ __forceinline__ float bf_hi(unsigned u) { return __uint_as_float(u & 0xffff0000u); }
;     __device__ __forceinline__ void operator()(f32x4 (&acc)[2][2][4][2], const Unit& u, int wr, int wc, int fr, int fq) const {
;     ...
;                 for (int bj = 0; bj < 2; ++bj) { const u32x4 g = *(const GAS u32x4*)(gp + bj * HALF);
;                     f32x4 s0 = {bf_lo(g.x), bf_hi(g.x), bf_lo(g.y), bf_hi(g.y)}, s1 = {bf_lo(g.z), bf_hi(g.z), bf_lo(g.w), bf_hi(g.w)};
;                     if (br < 2) { const u32x4 h = *(const GAS u32x4*)(gn + bj * HALF);
;                         const f32x4 d0 = {bf_lo(h.x), bf_hi(h.x), bf_lo(h.y), bf_hi(h.y)}, d1 = {bf_lo(h.z), bf_hi(h.z), bf_lo(h.w), bf_hi(h.w)};
; #pragma unroll
;                         for (int e = 0; e < 4; ++e) { s0[e] *= __builtin_amdgcn_rcpf(fmaxf(d0[e], 1e-30f)); s1[e] *= __builtin_amdgcn_rcpf(fmaxf(d1[e], 1e-30f)); }
;                         acc[ai][bj][m][0] *= s0; acc[ai][bj][m][1] *= s1;
.LBB0_519:
	v_lshl_add_u64 v[148:149], s[20:21], 0, v[148:149]
	s_andn2_b64 vcc, exec, s[6:7]
	v_lshl_add_u64 v[148:149], v[148:149], 0, v[0:1]
	s_cbranch_vccnz .LBB0_521
	s_nop 1
	ds_bpermute_b32 v162, v244, v204
	ds_bpermute_b32 v163, v244, v205
	ds_bpermute_b32 v164, v244, v206
	ds_bpermute_b32 v165, v244, v207
	s_waitcnt lgkmcnt(0)
	v_lshlrev_b32_e32 v193, 16, v163
	v_and_b32_e32 v194, 0xffff0000, v163
	v_lshlrev_b32_e32 v163, 16, v164
	v_lshlrev_b32_e32 v182, 16, v162
	v_and_b32_e32 v192, 0xffff0000, v162
	v_max_f32_e32 v163, 0xda24260, v163
	v_and_b32_e32 v195, 0xffff0000, v164
	v_rcp_f32_e32 v164, v163
	v_max_f32_e32 v162, 0xda24260, v182
	v_max_f32_e32 v163, 0xda24260, v192
	v_rcp_f32_e32 v162, v162
	v_rcp_f32_e32 v163, v163
	v_lshlrev_b32_e32 v196, 16, v165
	v_and_b32_e32 v197, 0xffff0000, v165
	v_pk_mul_f32 v[156:157], v[162:163], v[156:157]
	v_max_f32_e32 v162, 0xda24260, v195
	v_rcp_f32_e32 v165, v162
	v_max_f32_e32 v163, 0xda24260, v196
	v_pk_mul_f32 v[154:155], v[164:165], v[154:155]
	v_rcp_f32_e32 v164, v163
	v_max_f32_e32 v162, 0xda24260, v193
	v_max_f32_e32 v163, 0xda24260, v194
	v_rcp_f32_e32 v162, v162
	v_rcp_f32_e32 v163, v163
	v_pk_mul_f32 v[128:129], v[128:129], v[156:157]
	v_pk_mul_f32 v[124:125], v[124:125], v[154:155]
	v_pk_mul_f32 v[152:153], v[162:163], v[152:153]
	v_max_f32_e32 v162, 0xda24260, v197
	v_rcp_f32_e32 v165, v162
	v_pk_mul_f32 v[130:131], v[130:131], v[152:153]
	v_pk_mul_f32 v[150:151], v[164:165], v[150:151]
	s_nop 0
	v_pk_mul_f32 v[126:127], v[126:127], v[150:151]

; #define GAS __attribute__((address_space(1)))
; __device__ __forceinline__ float bf_lo(unsigned u) { return __uint_as_float(u << 16); }
; __device__ __forceinline__ float bf_hi(unsigned u) { return __uint_as_float(u & 0xffff0000u); }
;     __device__ __forceinline__ void operator()(f32x4 (&acc)[2][2][4][2], const Unit& u, int wr, int wc, int fr, int fq) const {
;     ...
;                 for (int bj = 0; bj < 2; ++bj) { const u32x4 g = *(const GAS u32x4*)(gp + bj * HALF);
;                     f32x4 s0 = {bf_lo(g.x), bf_hi(g.x), bf_lo(g.y), bf_hi(g.y)}, s1 = {bf_lo(g.z), bf_hi(g.z), bf_lo(g.w), bf_hi(g.w)};
;                     if (br < 2) { const u32x4 h = *(const GAS u32x4*)(gn + bj * HALF);
;                         const f32x4 d0 = {bf_lo(h.x), bf_hi(h.x), bf_lo(h.y), bf_hi(h.y)}, d1 = {bf_lo(h.z), bf_hi(h.z), bf_lo(h.w), bf_hi(h.w)};
; #pragma unroll
;                         for (int e = 0; e < 4; ++e) { s0[e] *= __builtin_amdgcn_rcpf(fmaxf(d0[e], 1e-30f)); s1[e] *= __builtin_amdgcn_rcpf(fmaxf(d1[e], 1e-30f)); }
;                         acc[ai][bj][m][0] *= s0; acc[ai][bj][m][1] *= s1;
.LBB0_523:
	s_andn2_b64 vcc, exec, s[24:25]
	s_cbranch_vccnz .LBB0_525
	s_nop 1
	ds_bpermute_b32 v162, v244, v212
	ds_bpermute_b32 v163, v244, v213
	ds_bpermute_b32 v164, v244, v214
	ds_bpermute_b32 v165, v244, v215
	s_waitcnt lgkmcnt(0)
	v_lshlrev_b32_e32 v148, 16, v164
	v_and_b32_e32 v149, 0xffff0000, v164
	v_lshlrev_b32_e32 v144, 16, v162
	v_and_b32_e32 v145, 0xffff0000, v162
	v_max_f32_e32 v148, 0xda24260, v148
	v_max_f32_e32 v149, 0xda24260, v149
	v_rcp_f32_e32 v148, v148
	v_rcp_f32_e32 v149, v149
	v_max_f32_e32 v144, 0xda24260, v144
	v_max_f32_e32 v145, 0xda24260, v145
	v_rcp_f32_e32 v144, v144
	v_rcp_f32_e32 v145, v145
	v_lshlrev_b32_e32 v162, 16, v165
	v_pk_mul_f32 v[148:149], v[148:149], v[152:153]
	v_lshlrev_b32_e32 v156, 16, v163
	v_and_b32_e32 v157, 0xffff0000, v163
	v_max_f32_e32 v153, 0xda24260, v162
	v_pk_mul_f32 v[144:145], v[144:145], v[154:155]
	v_rcp_f32_e32 v154, v153
	v_max_f32_e32 v152, 0xda24260, v156
	v_max_f32_e32 v153, 0xda24260, v157
	v_rcp_f32_e32 v152, v152
	v_rcp_f32_e32 v153, v153
	v_and_b32_e32 v163, 0xffff0000, v165
	v_pk_mul_f32 v[96:97], v[96:97], v[144:145]
	v_pk_mul_f32 v[92:93], v[92:93], v[148:149]
	v_pk_mul_f32 v[150:151], v[152:153], v[150:151]
	v_max_f32_e32 v152, 0xda24260, v163
	v_rcp_f32_e32 v155, v152
	v_pk_mul_f32 v[98:99], v[98:99], v[150:151]
	v_pk_mul_f32 v[146:147], v[154:155], v[146:147]
	s_nop 0
	v_pk_mul_f32 v[94:95], v[94:95], v[146:147]

; #define GAS __attribute__((address_space(1)))
; __device__ __forceinline__ float bf_lo(unsigned u) { return __uint_as_float(u << 16); }
; __device__ __forceinline__ float bf_hi(unsigned u) { return __uint_as_float(u & 0xffff0000u); }
;     __device__ __forceinline__ void operator()(f32x4 (&acc)[2][2][4][2], const Unit& u, int wr, int wc, int fr, int fq) const {
;     ...
;                 for (int bj = 0; bj < 2; ++bj) { const u32x4 g = *(const GAS u32x4*)(gp + bj * HALF);
;                     f32x4 s0 = {bf_lo(g.x), bf_hi(g.x), bf_lo(g.y), bf_hi(g.y)}, s1 = {bf_lo(g.z), bf_hi(g.z), bf_lo(g.w), bf_hi(g.w)};
;                     if (br < 2) { const u32x4 h = *(const GAS u32x4*)(gn + bj * HALF);
;                         const f32x4 d0 = {bf_lo(h.x), bf_hi(h.x), bf_lo(h.y), bf_hi(h.y)}, d1 = {bf_lo(h.z), bf_hi(h.z), bf_lo(h.w), bf_hi(h.w)};
; #pragma unroll
;                         for (int e = 0; e < 4; ++e) { s0[e] *= __builtin_amdgcn_rcpf(fmaxf(d0[e], 1e-30f)); s1[e] *= __builtin_amdgcn_rcpf(fmaxf(d1[e], 1e-30f)); }
;                         acc[ai][bj][m][0] *= s0; acc[ai][bj][m][1] *= s1;
.LBB0_527:
	v_lshl_add_u64 v[148:149], s[20:21], 0, v[148:149]
	s_andn2_b64 vcc, exec, s[24:25]
	v_lshl_add_u64 v[148:149], v[148:149], 0, v[0:1]
	s_cbranch_vccnz .LBB0_529
	s_nop 1
	ds_bpermute_b32 v162, v244, v220
	ds_bpermute_b32 v163, v244, v221
	ds_bpermute_b32 v164, v244, v222
	ds_bpermute_b32 v165, v244, v223
	s_waitcnt lgkmcnt(0)
	v_lshlrev_b32_e32 v193, 16, v163
	v_and_b32_e32 v194, 0xffff0000, v163
	v_lshlrev_b32_e32 v163, 16, v164
	v_lshlrev_b32_e32 v182, 16, v162
	v_and_b32_e32 v192, 0xffff0000, v162
	v_max_f32_e32 v163, 0xda24260, v163
	v_and_b32_e32 v195, 0xffff0000, v164
	v_rcp_f32_e32 v164, v163
	v_max_f32_e32 v162, 0xda24260, v182
	v_max_f32_e32 v163, 0xda24260, v192
	v_rcp_f32_e32 v162, v162
	v_rcp_f32_e32 v163, v163
	v_lshlrev_b32_e32 v196, 16, v165
	v_and_b32_e32 v197, 0xffff0000, v165
	v_pk_mul_f32 v[156:157], v[162:163], v[156:157]
	v_max_f32_e32 v162, 0xda24260, v195
	v_rcp_f32_e32 v165, v162
	v_max_f32_e32 v163, 0xda24260, v196
	v_pk_mul_f32 v[154:155], v[164:165], v[154:155]
	v_rcp_f32_e32 v164, v163
	v_max_f32_e32 v162, 0xda24260, v193
	v_max_f32_e32 v163, 0xda24260, v194
	v_rcp_f32_e32 v162, v162
	v_rcp_f32_e32 v163, v163
	v_pk_mul_f32 v[120:121], v[120:121], v[156:157]
	v_pk_mul_f32 v[116:117], v[116:117], v[154:155]
	v_pk_mul_f32 v[152:153], v[162:163], v[152:153]
	v_max_f32_e32 v162, 0xda24260, v197
	v_rcp_f32_e32 v165, v162
	v_pk_mul_f32 v[122:123], v[122:123], v[152:153]
	v_pk_mul_f32 v[150:151], v[164:165], v[150:151]
	s_nop 0
	v_pk_mul_f32 v[118:119], v[118:119], v[150:151]

; #define GAS __attribute__((address_space(1)))
; __device__ __forceinline__ float bf_lo(unsigned u) { return __uint_as_float(u << 16); }
; __device__ __forceinline__ float bf_hi(unsigned u) { return __uint_as_float(u & 0xffff0000u); }
;     __device__ __forceinline__ void operator()(f32x4 (&acc)[2][2][4][2], const Unit& u, int wr, int wc, int fr, int fq) const {
;     ...
;                 for (int bj = 0; bj < 2; ++bj) { const u32x4 g = *(const GAS u32x4*)(gp + bj * HALF);
;                     f32x4 s0 = {bf_lo(g.x), bf_hi(g.x), bf_lo(g.y), bf_hi(g.y)}, s1 = {bf_lo(g.z), bf_hi(g.z), bf_lo(g.w), bf_hi(g.w)};
;                     if (br < 2) { const u32x4 h = *(const GAS u32x4*)(gn + bj * HALF);
;                         const f32x4 d0 = {bf_lo(h.x), bf_hi(h.x), bf_lo(h.y), bf_hi(h.y)}, d1 = {bf_lo(h.z), bf_hi(h.z), bf_lo(h.w), bf_hi(h.w)};
; #pragma unroll
;                         for (int e = 0; e < 4; ++e) { s0[e] *= __builtin_amdgcn_rcpf(fmaxf(d0[e], 1e-30f)); s1[e] *= __builtin_amdgcn_rcpf(fmaxf(d1[e], 1e-30f)); }
;                         acc[ai][bj][m][0] *= s0; acc[ai][bj][m][1] *= s1;
.LBB0_531:
	s_andn2_b64 vcc, exec, s[24:25]
	s_cbranch_vccnz .LBB0_533
	s_nop 1
	ds_bpermute_b32 v162, v244, v228
	ds_bpermute_b32 v163, v244, v229
	ds_bpermute_b32 v164, v244, v230
	ds_bpermute_b32 v165, v244, v231
	s_waitcnt lgkmcnt(0)
	v_lshlrev_b32_e32 v148, 16, v164
	v_and_b32_e32 v149, 0xffff0000, v164
	v_lshlrev_b32_e32 v144, 16, v162
	v_and_b32_e32 v145, 0xffff0000, v162
	v_max_f32_e32 v148, 0xda24260, v148
	v_max_f32_e32 v149, 0xda24260, v149
	v_rcp_f32_e32 v148, v148
	v_rcp_f32_e32 v149, v149
	v_max_f32_e32 v144, 0xda24260, v144
	v_max_f32_e32 v145, 0xda24260, v145
	v_rcp_f32_e32 v144, v144
	v_rcp_f32_e32 v145, v145
	v_lshlrev_b32_e32 v162, 16, v165
	v_pk_mul_f32 v[148:149], v[148:149], v[152:153]
	v_lshlrev_b32_e32 v156, 16, v163
	v_and_b32_e32 v157, 0xffff0000, v163
	v_max_f32_e32 v153, 0xda24260, v162
	v_pk_mul_f32 v[144:145], v[144:145], v[154:155]
	v_rcp_f32_e32 v154, v153
	v_max_f32_e32 v152, 0xda24260, v156
	v_max_f32_e32 v153, 0xda24260, v157
	v_rcp_f32_e32 v152, v152
	v_rcp_f32_e32 v153, v153
	v_and_b32_e32 v163, 0xffff0000, v165
	v_pk_mul_f32 v[88:89], v[88:89], v[144:145]
	v_pk_mul_f32 v[84:85], v[84:85], v[148:149]
	v_pk_mul_f32 v[150:151], v[152:153], v[150:151]
	v_max_f32_e32 v152, 0xda24260, v163
	v_rcp_f32_e32 v155, v152
	v_pk_mul_f32 v[90:91], v[90:91], v[150:151]
	v_pk_mul_f32 v[146:147], v[154:155], v[146:147]
	s_nop 0
	v_pk_mul_f32 v[86:87], v[86:87], v[146:147]

; #define GAS __attribute__((address_space(1)))
; __device__ __forceinline__ float bf_lo(unsigned u) { return __uint_as_float(u << 16); }
; __device__ __forceinline__ float bf_hi(unsigned u) { return __uint_as_float(u & 0xffff0000u); }
;     __device__ __forceinline__ void operator()(f32x4 (&acc)[2][2][4][2], const Unit& u, int wr, int wc, int fr, int fq) const {
;     ...
;                 for (int bj = 0; bj < 2; ++bj) { const u32x4 g = *(const GAS u32x4*)(gp + bj * HALF);
;                     f32x4 s0 = {bf_lo(g.x), bf_hi(g.x), bf_lo(g.y), bf_hi(g.y)}, s1 = {bf_lo(g.z), bf_hi(g.z), bf_lo(g.w), bf_hi(g.w)};
;                     if (br < 2) { const u32x4 h = *(const GAS u32x4*)(gn + bj * HALF);
;                         const f32x4 d0 = {bf_lo(h.x), bf_hi(h.x), bf_lo(h.y), bf_hi(h.y)}, d1 = {bf_lo(h.z), bf_hi(h.z), bf_lo(h.w), bf_hi(h.w)};
; #pragma unroll
;                         for (int e = 0; e < 4; ++e) { s0[e] *= __builtin_amdgcn_rcpf(fmaxf(d0[e], 1e-30f)); s1[e] *= __builtin_amdgcn_rcpf(fmaxf(d1[e], 1e-30f)); }
;                         acc[ai][bj][m][0] *= s0; acc[ai][bj][m][1] *= s1;
.LBB0_535:
	v_lshl_add_u64 v[148:149], s[20:21], 0, v[148:149]
	s_andn2_b64 vcc, exec, s[24:25]
	v_lshl_add_u64 v[148:149], v[148:149], 0, v[0:1]
	s_cbranch_vccnz .LBB0_537
	s_nop 1
	ds_bpermute_b32 v162, v244, v204
	ds_bpermute_b32 v163, v244, v205
	ds_bpermute_b32 v164, v244, v206
	ds_bpermute_b32 v165, v244, v207
	s_waitcnt lgkmcnt(0)
	v_lshlrev_b32_e32 v193, 16, v163
	v_and_b32_e32 v194, 0xffff0000, v163
	v_lshlrev_b32_e32 v163, 16, v164
	v_lshlrev_b32_e32 v182, 16, v162
	v_and_b32_e32 v192, 0xffff0000, v162
	v_max_f32_e32 v163, 0xda24260, v163
	v_and_b32_e32 v195, 0xffff0000, v164
	v_rcp_f32_e32 v164, v163
	v_max_f32_e32 v162, 0xda24260, v182
	v_max_f32_e32 v163, 0xda24260, v192
	v_rcp_f32_e32 v162, v162
	v_rcp_f32_e32 v163, v163
	v_lshlrev_b32_e32 v196, 16, v165
	v_and_b32_e32 v197, 0xffff0000, v165
	v_pk_mul_f32 v[156:157], v[162:163], v[156:157]
	v_max_f32_e32 v162, 0xda24260, v195
	v_rcp_f32_e32 v165, v162
	v_max_f32_e32 v163, 0xda24260, v196
	v_pk_mul_f32 v[154:155], v[164:165], v[154:155]
	v_rcp_f32_e32 v164, v163
	v_max_f32_e32 v162, 0xda24260, v193
	v_max_f32_e32 v163, 0xda24260, v194
	v_rcp_f32_e32 v162, v162
	v_rcp_f32_e32 v163, v163
	v_pk_mul_f32 v[112:113], v[112:113], v[156:157]
	v_pk_mul_f32 v[108:109], v[108:109], v[154:155]
	v_pk_mul_f32 v[152:153], v[162:163], v[152:153]
	v_max_f32_e32 v162, 0xda24260, v197
	v_rcp_f32_e32 v165, v162
	v_pk_mul_f32 v[114:115], v[114:115], v[152:153]
	v_pk_mul_f32 v[150:151], v[164:165], v[150:151]
	s_nop 0
	v_pk_mul_f32 v[110:111], v[110:111], v[150:151]

; #define GAS __attribute__((address_space(1)))
; __device__ __forceinline__ float bf_lo(unsigned u) { return __uint_as_float(u << 16); }
; __device__ __forceinline__ float bf_hi(unsigned u) { return __uint_as_float(u & 0xffff0000u); }
;     __device__ __forceinline__ void operator()(f32x4 (&acc)[2][2][4][2], const Unit& u, int wr, int wc, int fr, int fq) const {
;     ...
;                 for (int bj = 0; bj < 2; ++bj) { const u32x4 g = *(const GAS u32x4*)(gp + bj * HALF);
;                     f32x4 s0 = {bf_lo(g.x), bf_hi(g.x), bf_lo(g.y), bf_hi(g.y)}, s1 = {bf_lo(g.z), bf_hi(g.z), bf_lo(g.w), bf_hi(g.w)};
;                     if (br < 2) { const u32x4 h = *(const GAS u32x4*)(gn + bj * HALF);
;                         const f32x4 d0 = {bf_lo(h.x), bf_hi(h.x), bf_lo(h.y), bf_hi(h.y)}, d1 = {bf_lo(h.z), bf_hi(h.z), bf_lo(h.w), bf_hi(h.w)};
; #pragma unroll
;                         for (int e = 0; e < 4; ++e) { s0[e] *= __builtin_amdgcn_rcpf(fmaxf(d0[e], 1e-30f)); s1[e] *= __builtin_amdgcn_rcpf(fmaxf(d1[e], 1e-30f)); }
;                         acc[ai][bj][m][0] *= s0; acc[ai][bj][m][1] *= s1;
.LBB0_539:
	s_andn2_b64 vcc, exec, s[24:25]
	s_cbranch_vccnz .LBB0_541
	s_nop 1
	ds_bpermute_b32 v162, v244, v212
	ds_bpermute_b32 v163, v244, v213
	ds_bpermute_b32 v164, v244, v214
	ds_bpermute_b32 v165, v244, v215
	s_waitcnt lgkmcnt(0)
	v_lshlrev_b32_e32 v148, 16, v164
	v_and_b32_e32 v149, 0xffff0000, v164
	v_lshlrev_b32_e32 v144, 16, v162
	v_and_b32_e32 v145, 0xffff0000, v162
	v_max_f32_e32 v148, 0xda24260, v148
	v_max_f32_e32 v149, 0xda24260, v149
	v_rcp_f32_e32 v148, v148
	v_rcp_f32_e32 v149, v149
	v_max_f32_e32 v144, 0xda24260, v144
	v_max_f32_e32 v145, 0xda24260, v145
	v_rcp_f32_e32 v144, v144
	v_rcp_f32_e32 v145, v145
	v_lshlrev_b32_e32 v162, 16, v165
	v_pk_mul_f32 v[148:149], v[148:149], v[152:153]
	v_lshlrev_b32_e32 v156, 16, v163
	v_and_b32_e32 v157, 0xffff0000, v163
	v_max_f32_e32 v153, 0xda24260, v162
	v_pk_mul_f32 v[144:145], v[144:145], v[154:155]
	v_rcp_f32_e32 v154, v153
	v_max_f32_e32 v152, 0xda24260, v156
	v_max_f32_e32 v153, 0xda24260, v157
	v_rcp_f32_e32 v152, v152
	v_rcp_f32_e32 v153, v153
	v_and_b32_e32 v163, 0xffff0000, v165
	v_pk_mul_f32 v[80:81], v[80:81], v[144:145]
	v_pk_mul_f32 v[76:77], v[76:77], v[148:149]
	v_pk_mul_f32 v[150:151], v[152:153], v[150:151]
	v_max_f32_e32 v152, 0xda24260, v163
	v_rcp_f32_e32 v155, v152
	v_pk_mul_f32 v[82:83], v[82:83], v[150:151]
	v_pk_mul_f32 v[146:147], v[154:155], v[146:147]
	s_nop 0
	v_pk_mul_f32 v[78:79], v[78:79], v[146:147]

; #define GAS __attribute__((address_space(1)))
; __device__ __forceinline__ float bf_lo(unsigned u) { return __uint_as_float(u << 16); }
; __device__ __forceinline__ float bf_hi(unsigned u) { return __uint_as_float(u & 0xffff0000u); }
;     __device__ __forceinline__ void operator()(f32x4 (&acc)[2][2][4][2], const Unit& u, int wr, int wc, int fr, int fq) const {
;     ...
;                 for (int bj = 0; bj < 2; ++bj) { const u32x4 g = *(const GAS u32x4*)(gp + bj * HALF);
;                     f32x4 s0 = {bf_lo(g.x), bf_hi(g.x), bf_lo(g.y), bf_hi(g.y)}, s1 = {bf_lo(g.z), bf_hi(g.z), bf_lo(g.w), bf_hi(g.w)};
;                     if (br < 2) { const u32x4 h = *(const GAS u32x4*)(gn + bj * HALF);
;                         const f32x4 d0 = {bf_lo(h.x), bf_hi(h.x), bf_lo(h.y), bf_hi(h.y)}, d1 = {bf_lo(h.z), bf_hi(h.z), bf_lo(h.w), bf_hi(h.w)};
; #pragma unroll
;                         for (int e = 0; e < 4; ++e) { s0[e] *= __builtin_amdgcn_rcpf(fmaxf(d0[e], 1e-30f)); s1[e] *= __builtin_amdgcn_rcpf(fmaxf(d1[e], 1e-30f)); }
;                         acc[ai][bj][m][0] *= s0; acc[ai][bj][m][1] *= s1;
.LBB0_543:
	v_lshl_add_u64 v[148:149], s[20:21], 0, v[148:149]
	s_andn2_b64 vcc, exec, s[24:25]
	v_lshl_add_u64 v[148:149], v[148:149], 0, v[0:1]
	s_cbranch_vccnz .LBB0_545
	s_nop 1
	ds_bpermute_b32 v162, v244, v220
	ds_bpermute_b32 v163, v244, v221
	ds_bpermute_b32 v164, v244, v222
	ds_bpermute_b32 v165, v244, v223
	s_waitcnt lgkmcnt(0)
	v_lshlrev_b32_e32 v193, 16, v163
	v_and_b32_e32 v194, 0xffff0000, v163
	v_lshlrev_b32_e32 v163, 16, v164
	v_lshlrev_b32_e32 v182, 16, v162
	v_and_b32_e32 v192, 0xffff0000, v162
	v_max_f32_e32 v163, 0xda24260, v163
	v_and_b32_e32 v195, 0xffff0000, v164
	v_rcp_f32_e32 v164, v163
	v_max_f32_e32 v162, 0xda24260, v182
	v_max_f32_e32 v163, 0xda24260, v192
	v_rcp_f32_e32 v162, v162
	v_rcp_f32_e32 v163, v163
	v_lshlrev_b32_e32 v196, 16, v165
	v_and_b32_e32 v197, 0xffff0000, v165
	v_pk_mul_f32 v[156:157], v[162:163], v[156:157]
	v_max_f32_e32 v162, 0xda24260, v195
	v_rcp_f32_e32 v165, v162
	v_max_f32_e32 v163, 0xda24260, v196
	v_pk_mul_f32 v[154:155], v[164:165], v[154:155]
	v_rcp_f32_e32 v164, v163
	v_max_f32_e32 v162, 0xda24260, v193
	v_max_f32_e32 v163, 0xda24260, v194
	v_rcp_f32_e32 v162, v162
	v_rcp_f32_e32 v163, v163
	v_pk_mul_f32 v[104:105], v[104:105], v[156:157]
	v_pk_mul_f32 v[100:101], v[100:101], v[154:155]
	v_pk_mul_f32 v[152:153], v[162:163], v[152:153]
	v_max_f32_e32 v162, 0xda24260, v197
	v_rcp_f32_e32 v165, v162
	v_pk_mul_f32 v[106:107], v[106:107], v[152:153]
	v_pk_mul_f32 v[150:151], v[164:165], v[150:151]
	s_nop 0
	v_pk_mul_f32 v[102:103], v[102:103], v[150:151]

; #define GAS __attribute__((address_space(1)))
; __device__ __forceinline__ float bf_lo(unsigned u) { return __uint_as_float(u << 16); }
; __device__ __forceinline__ float bf_hi(unsigned u) { return __uint_as_float(u & 0xffff0000u); }
;     __device__ __forceinline__ void operator()(f32x4 (&acc)[2][2][4][2], const Unit& u, int wr, int wc, int fr, int fq) const {
;     ...
;                 for (int bj = 0; bj < 2; ++bj) { const u32x4 g = *(const GAS u32x4*)(gp + bj * HALF);
;                     f32x4 s0 = {bf_lo(g.x), bf_hi(g.x), bf_lo(g.y), bf_hi(g.y)}, s1 = {bf_lo(g.z), bf_hi(g.z), bf_lo(g.w), bf_hi(g.w)};
;                     if (br < 2) { const u32x4 h = *(const GAS u32x4*)(gn + bj * HALF);
;                         const f32x4 d0 = {bf_lo(h.x), bf_hi(h.x), bf_lo(h.y), bf_hi(h.y)}, d1 = {bf_lo(h.z), bf_hi(h.z), bf_lo(h.w), bf_hi(h.w)};
; #pragma unroll
;                         for (int e = 0; e < 4; ++e) { s0[e] *= __builtin_amdgcn_rcpf(fmaxf(d0[e], 1e-30f)); s1[e] *= __builtin_amdgcn_rcpf(fmaxf(d1[e], 1e-30f)); }
;                         acc[ai][bj][m][0] *= s0; acc[ai][bj][m][1] *= s1;
.LBB0_547:
	s_andn2_b64 vcc, exec, s[24:25]
	s_cbranch_vccnz .LBB0_549
	s_nop 1
	ds_bpermute_b32 v162, v244, v228
	ds_bpermute_b32 v163, v244, v229
	ds_bpermute_b32 v164, v244, v230
	ds_bpermute_b32 v165, v244, v231
	s_waitcnt lgkmcnt(0)
	v_lshlrev_b32_e32 v148, 16, v164
	v_and_b32_e32 v149, 0xffff0000, v164
	v_lshlrev_b32_e32 v144, 16, v162
	v_and_b32_e32 v145, 0xffff0000, v162
	v_max_f32_e32 v148, 0xda24260, v148
	v_max_f32_e32 v149, 0xda24260, v149
	v_rcp_f32_e32 v148, v148
	v_rcp_f32_e32 v149, v149
	v_max_f32_e32 v144, 0xda24260, v144
	v_max_f32_e32 v145, 0xda24260, v145
	v_rcp_f32_e32 v144, v144
	v_rcp_f32_e32 v145, v145
	v_lshlrev_b32_e32 v162, 16, v165
	v_pk_mul_f32 v[148:149], v[148:149], v[152:153]
	v_lshlrev_b32_e32 v156, 16, v163
	v_and_b32_e32 v157, 0xffff0000, v163
	v_max_f32_e32 v153, 0xda24260, v162
	v_pk_mul_f32 v[144:145], v[144:145], v[154:155]
	v_rcp_f32_e32 v154, v153
	v_max_f32_e32 v152, 0xda24260, v156
	v_max_f32_e32 v153, 0xda24260, v157
	v_rcp_f32_e32 v152, v152
	v_rcp_f32_e32 v153, v153
	v_and_b32_e32 v163, 0xffff0000, v165
	v_pk_mul_f32 v[72:73], v[72:73], v[144:145]
	v_pk_mul_f32 v[68:69], v[68:69], v[148:149]
	v_pk_mul_f32 v[150:151], v[152:153], v[150:151]
	v_max_f32_e32 v152, 0xda24260, v163
	v_rcp_f32_e32 v155, v152
	v_pk_mul_f32 v[74:75], v[74:75], v[150:151]
	v_pk_mul_f32 v[146:147], v[154:155], v[146:147]
	s_nop 0
	v_pk_mul_f32 v[70:71], v[70:71], v[146:147]

; #define GAS __attribute__((address_space(1)))
; __device__ __forceinline__ float bf_lo(unsigned u) { return __uint_as_float(u << 16); }
; __device__ __forceinline__ float bf_hi(unsigned u) { return __uint_as_float(u & 0xffff0000u); }
;     __device__ __forceinline__ void operator()(f32x4 (&acc)[2][2][4][2], const Unit& u, int wr, int wc, int fr, int fq) const {
;     ...
;                 for (int bj = 0; bj < 2; ++bj) { const u32x4 g = *(const GAS u32x4*)(gp + bj * HALF);
;                     f32x4 s0 = {bf_lo(g.x), bf_hi(g.x), bf_lo(g.y), bf_hi(g.y)}, s1 = {bf_lo(g.z), bf_hi(g.z), bf_lo(g.w), bf_hi(g.w)};
;                     if (br < 2) { const u32x4 h = *(const GAS u32x4*)(gn + bj * HALF);
;                         const f32x4 d0 = {bf_lo(h.x), bf_hi(h.x), bf_lo(h.y), bf_hi(h.y)}, d1 = {bf_lo(h.z), bf_hi(h.z), bf_lo(h.w), bf_hi(h.w)};
; #pragma unroll
;                         for (int e = 0; e < 4; ++e) { s0[e] *= __builtin_amdgcn_rcpf(fmaxf(d0[e], 1e-30f)); s1[e] *= __builtin_amdgcn_rcpf(fmaxf(d1[e], 1e-30f)); }
;                         acc[ai][bj][m][0] *= s0; acc[ai][bj][m][1] *= s1;
.LBB0_551:
	v_lshl_add_u64 v[148:149], s[20:21], 0, v[148:149]
	s_andn2_b64 vcc, exec, s[24:25]
	v_lshl_add_u64 v[148:149], v[148:149], 0, v[0:1]
	s_cbranch_vccnz .LBB0_553
	s_nop 1
	ds_bpermute_b32 v162, v244, v204
	ds_bpermute_b32 v163, v244, v205
	ds_bpermute_b32 v164, v244, v206
	ds_bpermute_b32 v165, v244, v207
	s_waitcnt lgkmcnt(0)
	v_lshlrev_b32_e32 v193, 16, v163
	v_and_b32_e32 v194, 0xffff0000, v163
	v_lshlrev_b32_e32 v163, 16, v164
	v_lshlrev_b32_e32 v182, 16, v162
	v_and_b32_e32 v192, 0xffff0000, v162
	v_max_f32_e32 v163, 0xda24260, v163
	v_and_b32_e32 v195, 0xffff0000, v164
	v_rcp_f32_e32 v164, v163
	v_max_f32_e32 v162, 0xda24260, v182
	v_max_f32_e32 v163, 0xda24260, v192
	v_rcp_f32_e32 v162, v162
	v_rcp_f32_e32 v163, v163
	v_lshlrev_b32_e32 v196, 16, v165
	v_and_b32_e32 v197, 0xffff0000, v165
	v_pk_mul_f32 v[156:157], v[162:163], v[156:157]
	v_max_f32_e32 v162, 0xda24260, v195
	v_rcp_f32_e32 v165, v162
	v_max_f32_e32 v163, 0xda24260, v196
	v_pk_mul_f32 v[154:155], v[164:165], v[154:155]
	v_rcp_f32_e32 v164, v163
	v_max_f32_e32 v162, 0xda24260, v193
	v_max_f32_e32 v163, 0xda24260, v194
	v_rcp_f32_e32 v162, v162
	v_rcp_f32_e32 v163, v163
	v_pk_mul_f32 v[64:65], v[64:65], v[156:157]
	v_pk_mul_f32 v[60:61], v[60:61], v[154:155]
	v_pk_mul_f32 v[152:153], v[162:163], v[152:153]
	v_max_f32_e32 v162, 0xda24260, v197
	v_rcp_f32_e32 v165, v162
	v_pk_mul_f32 v[66:67], v[66:67], v[152:153]
	v_pk_mul_f32 v[150:151], v[164:165], v[150:151]
	s_nop 0
	v_pk_mul_f32 v[62:63], v[62:63], v[150:151]

; #define GAS __attribute__((address_space(1)))
; __device__ __forceinline__ float bf_lo(unsigned u) { return __uint_as_float(u << 16); }
; __device__ __forceinline__ float bf_hi(unsigned u) { return __uint_as_float(u & 0xffff0000u); }
;     __device__ __forceinline__ void operator()(f32x4 (&acc)[2][2][4][2], const Unit& u, int wr, int wc, int fr, int fq) const {
;     ...
;                 for (int bj = 0; bj < 2; ++bj) { const u32x4 g = *(const GAS u32x4*)(gp + bj * HALF);
;                     f32x4 s0 = {bf_lo(g.x), bf_hi(g.x), bf_lo(g.y), bf_hi(g.y)}, s1 = {bf_lo(g.z), bf_hi(g.z), bf_lo(g.w), bf_hi(g.w)};
;                     if (br < 2) { const u32x4 h = *(const GAS u32x4*)(gn + bj * HALF);
;                         const f32x4 d0 = {bf_lo(h.x), bf_hi(h.x), bf_lo(h.y), bf_hi(h.y)}, d1 = {bf_lo(h.z), bf_hi(h.z), bf_lo(h.w), bf_hi(h.w)};
; #pragma unroll
;                         for (int e = 0; e < 4; ++e) { s0[e] *= __builtin_amdgcn_rcpf(fmaxf(d0[e], 1e-30f)); s1[e] *= __builtin_amdgcn_rcpf(fmaxf(d1[e], 1e-30f)); }
;                         acc[ai][bj][m][0] *= s0; acc[ai][bj][m][1] *= s1;
.LBB0_555:
	s_andn2_b64 vcc, exec, s[24:25]
	s_cbranch_vccnz .LBB0_557
	s_nop 1
	ds_bpermute_b32 v162, v244, v212
	ds_bpermute_b32 v163, v244, v213
	ds_bpermute_b32 v164, v244, v214
	ds_bpermute_b32 v165, v244, v215
	s_waitcnt lgkmcnt(0)
	v_lshlrev_b32_e32 v148, 16, v164
	v_and_b32_e32 v149, 0xffff0000, v164
	v_lshlrev_b32_e32 v144, 16, v162
	v_and_b32_e32 v145, 0xffff0000, v162
	v_max_f32_e32 v148, 0xda24260, v148
	v_max_f32_e32 v149, 0xda24260, v149
	v_rcp_f32_e32 v148, v148
	v_rcp_f32_e32 v149, v149
	v_max_f32_e32 v144, 0xda24260, v144
	v_max_f32_e32 v145, 0xda24260, v145
	v_rcp_f32_e32 v144, v144
	v_rcp_f32_e32 v145, v145
	v_lshlrev_b32_e32 v162, 16, v165
	v_pk_mul_f32 v[148:149], v[148:149], v[152:153]
	v_lshlrev_b32_e32 v156, 16, v163
	v_and_b32_e32 v157, 0xffff0000, v163
	v_max_f32_e32 v153, 0xda24260, v162
	v_pk_mul_f32 v[144:145], v[144:145], v[154:155]
	v_rcp_f32_e32 v154, v153
	v_max_f32_e32 v152, 0xda24260, v156
	v_max_f32_e32 v153, 0xda24260, v157
	v_rcp_f32_e32 v152, v152
	v_rcp_f32_e32 v153, v153
	v_and_b32_e32 v163, 0xffff0000, v165
	v_pk_mul_f32 v[32:33], v[32:33], v[144:145]
	v_pk_mul_f32 v[28:29], v[28:29], v[148:149]
	v_pk_mul_f32 v[150:151], v[152:153], v[150:151]
	v_max_f32_e32 v152, 0xda24260, v163
	v_rcp_f32_e32 v155, v152
	v_pk_mul_f32 v[34:35], v[34:35], v[150:151]
	v_pk_mul_f32 v[146:147], v[154:155], v[146:147]
	s_nop 0
	v_pk_mul_f32 v[30:31], v[30:31], v[146:147]

; #define GAS __attribute__((address_space(1)))
; __device__ __forceinline__ float bf_lo(unsigned u) { return __uint_as_float(u << 16); }
; __device__ __forceinline__ float bf_hi(unsigned u) { return __uint_as_float(u & 0xffff0000u); }
;     __device__ __forceinline__ void operator()(f32x4 (&acc)[2][2][4][2], const Unit& u, int wr, int wc, int fr, int fq) const {
;     ...
;                 for (int bj = 0; bj < 2; ++bj) { const u32x4 g = *(const GAS u32x4*)(gp + bj * HALF);
;                     f32x4 s0 = {bf_lo(g.x), bf_hi(g.x), bf_lo(g.y), bf_hi(g.y)}, s1 = {bf_lo(g.z), bf_hi(g.z), bf_lo(g.w), bf_hi(g.w)};
;                     if (br < 2) { const u32x4 h = *(const GAS u32x4*)(gn + bj * HALF);
;                         const f32x4 d0 = {bf_lo(h.x), bf_hi(h.x), bf_lo(h.y), bf_hi(h.y)}, d1 = {bf_lo(h.z), bf_hi(h.z), bf_lo(h.w), bf_hi(h.w)};
; #pragma unroll
;                         for (int e = 0; e < 4; ++e) { s0[e] *= __builtin_amdgcn_rcpf(fmaxf(d0[e], 1e-30f)); s1[e] *= __builtin_amdgcn_rcpf(fmaxf(d1[e], 1e-30f)); }
;                         acc[ai][bj][m][0] *= s0; acc[ai][bj][m][1] *= s1;
.LBB0_559:
	v_lshl_add_u64 v[148:149], s[20:21], 0, v[148:149]
	s_andn2_b64 vcc, exec, s[24:25]
	v_lshl_add_u64 v[148:149], v[148:149], 0, v[0:1]
	s_cbranch_vccnz .LBB0_561
	s_nop 1
	ds_bpermute_b32 v162, v244, v220
	ds_bpermute_b32 v163, v244, v221
	ds_bpermute_b32 v164, v244, v222
	ds_bpermute_b32 v165, v244, v223
	s_waitcnt lgkmcnt(0)
	v_lshlrev_b32_e32 v193, 16, v163
	v_and_b32_e32 v194, 0xffff0000, v163
	v_lshlrev_b32_e32 v163, 16, v164
	v_lshlrev_b32_e32 v182, 16, v162
	v_and_b32_e32 v192, 0xffff0000, v162
	v_max_f32_e32 v163, 0xda24260, v163
	v_and_b32_e32 v195, 0xffff0000, v164
	v_rcp_f32_e32 v164, v163
	v_max_f32_e32 v162, 0xda24260, v182
	v_max_f32_e32 v163, 0xda24260, v192
	v_rcp_f32_e32 v162, v162
	v_rcp_f32_e32 v163, v163
	v_lshlrev_b32_e32 v196, 16, v165
	v_and_b32_e32 v197, 0xffff0000, v165
	v_pk_mul_f32 v[156:157], v[162:163], v[156:157]
	v_max_f32_e32 v162, 0xda24260, v195
	v_rcp_f32_e32 v165, v162
	v_max_f32_e32 v163, 0xda24260, v196
	v_pk_mul_f32 v[154:155], v[164:165], v[154:155]
	v_rcp_f32_e32 v164, v163
	v_max_f32_e32 v162, 0xda24260, v193
	v_max_f32_e32 v163, 0xda24260, v194
	v_rcp_f32_e32 v162, v162
	v_rcp_f32_e32 v163, v163
	v_pk_mul_f32 v[56:57], v[56:57], v[156:157]
	v_pk_mul_f32 v[52:53], v[52:53], v[154:155]
	v_pk_mul_f32 v[152:153], v[162:163], v[152:153]
	v_max_f32_e32 v162, 0xda24260, v197
	v_rcp_f32_e32 v165, v162
	v_pk_mul_f32 v[58:59], v[58:59], v[152:153]
	v_pk_mul_f32 v[150:151], v[164:165], v[150:151]
	s_nop 0
	v_pk_mul_f32 v[54:55], v[54:55], v[150:151]

; #define GAS __attribute__((address_space(1)))
; __device__ __forceinline__ float bf_lo(unsigned u) { return __uint_as_float(u << 16); }
; __device__ __forceinline__ float bf_hi(unsigned u) { return __uint_as_float(u & 0xffff0000u); }
;     __device__ __forceinline__ void operator()(f32x4 (&acc)[2][2][4][2], const Unit& u, int wr, int wc, int fr, int fq) const {
;     ...
;                 for (int bj = 0; bj < 2; ++bj) { const u32x4 g = *(const GAS u32x4*)(gp + bj * HALF);
;                     f32x4 s0 = {bf_lo(g.x), bf_hi(g.x), bf_lo(g.y), bf_hi(g.y)}, s1 = {bf_lo(g.z), bf_hi(g.z), bf_lo(g.w), bf_hi(g.w)};
;                     if (br < 2) { const u32x4 h = *(const GAS u32x4*)(gn + bj * HALF);
;                         const f32x4 d0 = {bf_lo(h.x), bf_hi(h.x), bf_lo(h.y), bf_hi(h.y)}, d1 = {bf_lo(h.z), bf_hi(h.z), bf_lo(h.w), bf_hi(h.w)};
; #pragma unroll
;                         for (int e = 0; e < 4; ++e) { s0[e] *= __builtin_amdgcn_rcpf(fmaxf(d0[e], 1e-30f)); s1[e] *= __builtin_amdgcn_rcpf(fmaxf(d1[e], 1e-30f)); }
;                         acc[ai][bj][m][0] *= s0; acc[ai][bj][m][1] *= s1;
.LBB0_563:
	s_andn2_b64 vcc, exec, s[24:25]
	s_cbranch_vccnz .LBB0_565
	s_nop 1
	ds_bpermute_b32 v162, v244, v228
	ds_bpermute_b32 v163, v244, v229
	ds_bpermute_b32 v164, v244, v230
	ds_bpermute_b32 v165, v244, v231
	s_waitcnt lgkmcnt(0)
	v_lshlrev_b32_e32 v148, 16, v164
	v_and_b32_e32 v149, 0xffff0000, v164
	v_lshlrev_b32_e32 v144, 16, v162
	v_and_b32_e32 v145, 0xffff0000, v162
	v_max_f32_e32 v148, 0xda24260, v148
	v_max_f32_e32 v149, 0xda24260, v149
	v_rcp_f32_e32 v148, v148
	v_rcp_f32_e32 v149, v149
	v_max_f32_e32 v144, 0xda24260, v144
	v_max_f32_e32 v145, 0xda24260, v145
	v_rcp_f32_e32 v144, v144
	v_rcp_f32_e32 v145, v145
	v_lshlrev_b32_e32 v162, 16, v165
	v_pk_mul_f32 v[148:149], v[148:149], v[152:153]
	v_lshlrev_b32_e32 v156, 16, v163
	v_and_b32_e32 v157, 0xffff0000, v163
	v_max_f32_e32 v153, 0xda24260, v162
	v_pk_mul_f32 v[144:145], v[144:145], v[154:155]
	v_rcp_f32_e32 v154, v153
	v_max_f32_e32 v152, 0xda24260, v156
	v_max_f32_e32 v153, 0xda24260, v157
	v_rcp_f32_e32 v152, v152
	v_rcp_f32_e32 v153, v153
	v_and_b32_e32 v163, 0xffff0000, v165
	v_pk_mul_f32 v[24:25], v[24:25], v[144:145]
	v_pk_mul_f32 v[20:21], v[20:21], v[148:149]
	v_pk_mul_f32 v[150:151], v[152:153], v[150:151]
	v_max_f32_e32 v152, 0xda24260, v163
	v_rcp_f32_e32 v155, v152
	v_pk_mul_f32 v[26:27], v[26:27], v[150:151]
	v_pk_mul_f32 v[146:147], v[154:155], v[146:147]
	s_nop 0
	v_pk_mul_f32 v[22:23], v[22:23], v[146:147]

; #define GAS __attribute__((address_space(1)))
; __device__ __forceinline__ float bf_lo(unsigned u) { return __uint_as_float(u << 16); }
; __device__ __forceinline__ float bf_hi(unsigned u) { return __uint_as_float(u & 0xffff0000u); }
;     __device__ __forceinline__ void operator()(f32x4 (&acc)[2][2][4][2], const Unit& u, int wr, int wc, int fr, int fq) const {
;     ...
;                 for (int bj = 0; bj < 2; ++bj) { const u32x4 g = *(const GAS u32x4*)(gp + bj * HALF);
;                     f32x4 s0 = {bf_lo(g.x), bf_hi(g.x), bf_lo(g.y), bf_hi(g.y)}, s1 = {bf_lo(g.z), bf_hi(g.z), bf_lo(g.w), bf_hi(g.w)};
;                     if (br < 2) { const u32x4 h = *(const GAS u32x4*)(gn + bj * HALF);
;                         const f32x4 d0 = {bf_lo(h.x), bf_hi(h.x), bf_lo(h.y), bf_hi(h.y)}, d1 = {bf_lo(h.z), bf_hi(h.z), bf_lo(h.w), bf_hi(h.w)};
; #pragma unroll
;                         for (int e = 0; e < 4; ++e) { s0[e] *= __builtin_amdgcn_rcpf(fmaxf(d0[e], 1e-30f)); s1[e] *= __builtin_amdgcn_rcpf(fmaxf(d1[e], 1e-30f)); }
;                         acc[ai][bj][m][0] *= s0; acc[ai][bj][m][1] *= s1;
.LBB0_567:
	v_lshl_add_u64 v[148:149], s[20:21], 0, v[148:149]
	s_andn2_b64 vcc, exec, s[24:25]
	v_lshl_add_u64 v[148:149], v[148:149], 0, v[0:1]
	s_cbranch_vccnz .LBB0_569
	s_nop 1
	ds_bpermute_b32 v162, v244, v204
	ds_bpermute_b32 v163, v244, v205
	ds_bpermute_b32 v164, v244, v206
	ds_bpermute_b32 v165, v244, v207
	s_waitcnt lgkmcnt(0)
	v_lshlrev_b32_e32 v193, 16, v163
	v_and_b32_e32 v194, 0xffff0000, v163
	v_lshlrev_b32_e32 v163, 16, v164
	v_lshlrev_b32_e32 v182, 16, v162
	v_and_b32_e32 v192, 0xffff0000, v162
	v_max_f32_e32 v163, 0xda24260, v163
	v_and_b32_e32 v195, 0xffff0000, v164
	v_rcp_f32_e32 v164, v163
	v_max_f32_e32 v162, 0xda24260, v182
	v_max_f32_e32 v163, 0xda24260, v192
	v_rcp_f32_e32 v162, v162
	v_rcp_f32_e32 v163, v163
	v_lshlrev_b32_e32 v196, 16, v165
	v_and_b32_e32 v197, 0xffff0000, v165
	v_pk_mul_f32 v[156:157], v[162:163], v[156:157]
	v_max_f32_e32 v162, 0xda24260, v195
	v_rcp_f32_e32 v165, v162
	v_max_f32_e32 v163, 0xda24260, v196
	v_pk_mul_f32 v[154:155], v[164:165], v[154:155]
	v_rcp_f32_e32 v164, v163
	v_max_f32_e32 v162, 0xda24260, v193
	v_max_f32_e32 v163, 0xda24260, v194
	v_rcp_f32_e32 v162, v162
	v_rcp_f32_e32 v163, v163
	v_pk_mul_f32 v[48:49], v[48:49], v[156:157]
	v_pk_mul_f32 v[44:45], v[44:45], v[154:155]
	v_pk_mul_f32 v[152:153], v[162:163], v[152:153]
	v_max_f32_e32 v162, 0xda24260, v197
	v_rcp_f32_e32 v165, v162
	v_pk_mul_f32 v[50:51], v[50:51], v[152:153]
	v_pk_mul_f32 v[150:151], v[164:165], v[150:151]
	s_nop 0
	v_pk_mul_f32 v[46:47], v[46:47], v[150:151]

; #define GAS __attribute__((address_space(1)))
; __device__ __forceinline__ float bf_lo(unsigned u) { return __uint_as_float(u << 16); }
; __device__ __forceinline__ float bf_hi(unsigned u) { return __uint_as_float(u & 0xffff0000u); }
;     __device__ __forceinline__ void operator()(f32x4 (&acc)[2][2][4][2], const Unit& u, int wr, int wc, int fr, int fq) const {
;     ...
;                 for (int bj = 0; bj < 2; ++bj) { const u32x4 g = *(const GAS u32x4*)(gp + bj * HALF);
;                     f32x4 s0 = {bf_lo(g.x), bf_hi(g.x), bf_lo(g.y), bf_hi(g.y)}, s1 = {bf_lo(g.z), bf_hi(g.z), bf_lo(g.w), bf_hi(g.w)};
;                     if (br < 2) { const u32x4 h = *(const GAS u32x4*)(gn + bj * HALF);
;                         const f32x4 d0 = {bf_lo(h.x), bf_hi(h.x), bf_lo(h.y), bf_hi(h.y)}, d1 = {bf_lo(h.z), bf_hi(h.z), bf_lo(h.w), bf_hi(h.w)};
; #pragma unroll
;                         for (int e = 0; e < 4; ++e) { s0[e] *= __builtin_amdgcn_rcpf(fmaxf(d0[e], 1e-30f)); s1[e] *= __builtin_amdgcn_rcpf(fmaxf(d1[e], 1e-30f)); }
;                         acc[ai][bj][m][0] *= s0; acc[ai][bj][m][1] *= s1;
.LBB0_571:
	s_andn2_b64 vcc, exec, s[24:25]
	s_cbranch_vccnz .LBB0_573
	s_nop 1
	ds_bpermute_b32 v162, v244, v212
	ds_bpermute_b32 v163, v244, v213
	ds_bpermute_b32 v164, v244, v214
	ds_bpermute_b32 v165, v244, v215
	s_waitcnt lgkmcnt(0)
	v_lshlrev_b32_e32 v148, 16, v164
	v_and_b32_e32 v149, 0xffff0000, v164
	v_lshlrev_b32_e32 v144, 16, v162
	v_and_b32_e32 v145, 0xffff0000, v162
	v_max_f32_e32 v148, 0xda24260, v148
	v_max_f32_e32 v149, 0xda24260, v149
	v_rcp_f32_e32 v148, v148
	v_rcp_f32_e32 v149, v149
	v_max_f32_e32 v144, 0xda24260, v144
	v_max_f32_e32 v145, 0xda24260, v145
	v_rcp_f32_e32 v144, v144
	v_rcp_f32_e32 v145, v145
	v_lshlrev_b32_e32 v162, 16, v165
	v_pk_mul_f32 v[148:149], v[148:149], v[152:153]
	v_lshlrev_b32_e32 v156, 16, v163
	v_and_b32_e32 v157, 0xffff0000, v163
	v_max_f32_e32 v153, 0xda24260, v162
	v_pk_mul_f32 v[144:145], v[144:145], v[154:155]
	v_rcp_f32_e32 v154, v153
	v_max_f32_e32 v152, 0xda24260, v156
	v_max_f32_e32 v153, 0xda24260, v157
	v_rcp_f32_e32 v152, v152
	v_rcp_f32_e32 v153, v153
	v_and_b32_e32 v163, 0xffff0000, v165
	v_pk_mul_f32 v[16:17], v[16:17], v[144:145]
	v_pk_mul_f32 v[12:13], v[12:13], v[148:149]
	v_pk_mul_f32 v[150:151], v[152:153], v[150:151]
	v_max_f32_e32 v152, 0xda24260, v163
	v_rcp_f32_e32 v155, v152
	v_pk_mul_f32 v[18:19], v[18:19], v[150:151]
	v_pk_mul_f32 v[146:147], v[154:155], v[146:147]
	s_nop 0
	v_pk_mul_f32 v[14:15], v[14:15], v[146:147]

; #define GAS __attribute__((address_space(1)))
; __device__ __forceinline__ float bf_lo(unsigned u) { return __uint_as_float(u << 16); }
; __device__ __forceinline__ float bf_hi(unsigned u) { return __uint_as_float(u & 0xffff0000u); }
;     __device__ __forceinline__ void operator()(f32x4 (&acc)[2][2][4][2], const Unit& u, int wr, int wc, int fr, int fq) const {
;     ...
;                 for (int bj = 0; bj < 2; ++bj) { const u32x4 g = *(const GAS u32x4*)(gp + bj * HALF);
;                     f32x4 s0 = {bf_lo(g.x), bf_hi(g.x), bf_lo(g.y), bf_hi(g.y)}, s1 = {bf_lo(g.z), bf_hi(g.z), bf_lo(g.w), bf_hi(g.w)};
;                     if (br < 2) { const u32x4 h = *(const GAS u32x4*)(gn + bj * HALF);
;                         const f32x4 d0 = {bf_lo(h.x), bf_hi(h.x), bf_lo(h.y), bf_hi(h.y)}, d1 = {bf_lo(h.z), bf_hi(h.z), bf_lo(h.w), bf_hi(h.w)};
; #pragma unroll
;                         for (int e = 0; e < 4; ++e) { s0[e] *= __builtin_amdgcn_rcpf(fmaxf(d0[e], 1e-30f)); s1[e] *= __builtin_amdgcn_rcpf(fmaxf(d1[e], 1e-30f)); }
;                         acc[ai][bj][m][0] *= s0; acc[ai][bj][m][1] *= s1;
.LBB0_575:
	v_lshl_add_u64 v[146:147], s[20:21], 0, v[146:147]
	s_andn2_b64 vcc, exec, s[22:23]
	v_lshl_add_u64 v[146:147], v[146:147], 0, v[0:1]
	s_cbranch_vccnz .LBB0_577
	s_nop 1
	ds_bpermute_b32 v162, v244, v220
	ds_bpermute_b32 v163, v244, v221
	ds_bpermute_b32 v164, v244, v222
	ds_bpermute_b32 v165, v244, v223
	s_waitcnt lgkmcnt(0)
	v_lshlrev_b32_e32 v0, 16, v162
	v_and_b32_e32 v157, 0xffff0000, v162
	v_lshlrev_b32_e32 v162, 16, v164
	v_max_f32_e32 v0, 0xda24260, v0
	v_rcp_f32_e32 v156, v0
	v_max_f32_e32 v0, 0xda24260, v162
	v_rcp_f32_e32 v162, v0
	v_lshlrev_b32_e32 v182, 16, v163
	v_and_b32_e32 v192, 0xffff0000, v163
	v_and_b32_e32 v163, 0xffff0000, v164
	v_max_f32_e32 v0, 0xda24260, v157
	v_rcp_f32_e32 v157, v0
	v_max_f32_e32 v0, 0xda24260, v163
	v_rcp_f32_e32 v163, v0
	v_lshlrev_b32_e32 v164, 16, v165
	v_max_f32_e32 v0, 0xda24260, v182
	v_pk_mul_f32 v[154:155], v[156:157], v[154:155]
	v_rcp_f32_e32 v156, v0
	v_max_f32_e32 v0, 0xda24260, v164
	v_pk_mul_f32 v[152:153], v[162:163], v[152:153]
	v_rcp_f32_e32 v162, v0
	v_and_b32_e32 v165, 0xffff0000, v165
	v_max_f32_e32 v0, 0xda24260, v192
	v_rcp_f32_e32 v157, v0
	v_max_f32_e32 v0, 0xda24260, v165
	v_rcp_f32_e32 v163, v0
	v_pk_mul_f32 v[150:151], v[156:157], v[150:151]
	v_pk_mul_f32 v[40:41], v[40:41], v[154:155]
	v_pk_mul_f32 v[42:43], v[42:43], v[150:151]
	v_pk_mul_f32 v[148:149], v[162:163], v[148:149]
	v_pk_mul_f32 v[36:37], v[36:37], v[152:153]
	v_pk_mul_f32 v[38:39], v[38:39], v[148:149]

; #define GAS __attribute__((address_space(1)))
; __device__ __forceinline__ float bf_lo(unsigned u) { return __uint_as_float(u << 16); }
; __device__ __forceinline__ float bf_hi(unsigned u) { return __uint_as_float(u & 0xffff0000u); }
;     __device__ __forceinline__ void operator()(f32x4 (&acc)[2][2][4][2], const Unit& u, int wr, int wc, int fr, int fq) const {
;     ...
;                 for (int bj = 0; bj < 2; ++bj) { const u32x4 g = *(const GAS u32x4*)(gp + bj * HALF);
;                     f32x4 s0 = {bf_lo(g.x), bf_hi(g.x), bf_lo(g.y), bf_hi(g.y)}, s1 = {bf_lo(g.z), bf_hi(g.z), bf_lo(g.w), bf_hi(g.w)};
;                     if (br < 2) { const u32x4 h = *(const GAS u32x4*)(gn + bj * HALF);
;                         const f32x4 d0 = {bf_lo(h.x), bf_hi(h.x), bf_lo(h.y), bf_hi(h.y)}, d1 = {bf_lo(h.z), bf_hi(h.z), bf_lo(h.w), bf_hi(h.w)};
; #pragma unroll
;                         for (int e = 0; e < 4; ++e) { s0[e] *= __builtin_amdgcn_rcpf(fmaxf(d0[e], 1e-30f)); s1[e] *= __builtin_amdgcn_rcpf(fmaxf(d1[e], 1e-30f)); }
;                         acc[ai][bj][m][0] *= s0; acc[ai][bj][m][1] *= s1;
.LBB0_581:
	s_nop 1
	ds_bpermute_b32 v154, v244, v228
	ds_bpermute_b32 v155, v244, v229
	ds_bpermute_b32 v156, v244, v230
	ds_bpermute_b32 v157, v244, v231
	s_waitcnt lgkmcnt(0)
	v_lshlrev_b32_e32 v0, 16, v154
	v_lshlrev_b32_e32 v146, 16, v156
	v_max_f32_e32 v0, 0xda24260, v0
	v_rcp_f32_e32 v2, v0
	v_and_b32_e32 v3, 0xffff0000, v154
	v_max_f32_e32 v0, 0xda24260, v146
	v_rcp_f32_e32 v146, v0
	v_and_b32_e32 v147, 0xffff0000, v156
	v_max_f32_e32 v0, 0xda24260, v3
	v_rcp_f32_e32 v3, v0
	v_max_f32_e32 v0, 0xda24260, v147
	v_rcp_f32_e32 v147, v0
	v_lshlrev_b32_e32 v154, 16, v155
	v_lshlrev_b32_e32 v156, 16, v157
	v_max_f32_e32 v0, 0xda24260, v154
	v_pk_mul_f32 v[146:147], v[146:147], v[150:151]
	v_rcp_f32_e32 v150, v0
	v_and_b32_e32 v155, 0xffff0000, v155
	v_max_f32_e32 v0, 0xda24260, v156
	v_pk_mul_f32 v[2:3], v[2:3], v[152:153]
	v_rcp_f32_e32 v152, v0
	v_and_b32_e32 v157, 0xffff0000, v157
	v_max_f32_e32 v0, 0xda24260, v155
	v_rcp_f32_e32 v151, v0
	v_max_f32_e32 v0, 0xda24260, v157
	v_rcp_f32_e32 v153, v0
	v_pk_mul_f32 v[148:149], v[150:151], v[148:149]
	v_pk_mul_f32 v[8:9], v[8:9], v[2:3]
	v_pk_mul_f32 v[10:11], v[10:11], v[148:149]
	v_pk_mul_f32 v[144:145], v[152:153], v[144:145]
	v_pk_mul_f32 v[4:5], v[4:5], v[146:147]
	v_pk_mul_f32 v[6:7], v[6:7], v[144:145]
	s_andn2_b64 vcc, exec, s[18:19]
	s_mov_b64 s[6:7], -1
	s_cbranch_vccnz .LBB0_510

;     __device__ bool next(int i, Unit& u) const { const int j = i / 3, br = i - 3 * j; const int pmn = c + j * G; if (pmn >= 512) return false; u.pm = pmn >> 2; u.pn = br * 4 + (pmn & 3); return true; }
;     __device__ bool next(int i, Unit& u) const { const int j = i / 3, br = i - 3 * j; const int pmn = c + j * G; if (pmn >= 512) return false; u.pm = br * 128 + (pmn >> 2); u.pn = br * 4 + (pmn & 3); return true; }
; template <class Epi, class Sched, bool ALIGN_EPI = false, bool SP2 = false>
; __device__ __forceinline__ void gemm_phase(PG8_LAS unsigned char* lds, const Gemm g, const Sched& S, const Epi& E) {
;     ...
;         const bool has_next = S.next(ui + 1, nxt);
;         const char* nA = has_next ? (const char*)g.A + (size_t)nxt.pm * tstep : cA; const char* nB = has_next ? (const char*)g.Bt + (size_t)nxt.pn * tstep : cB;
;         for (int t = 0; t < nt; t += 2) {
;             const bool last = (t == nt - 2);
;             const char* a1 = cA + (size_t)(t + 1) * kstep;
;             const char* a2 = last ? nA : cA + (size_t)(t + 2) * kstep; const char* b2 = last ? nB : cB + (size_t)(t + 2) * kstep;
;     ...
;         for (int a = 0; a < 2; ++a)
; #pragma unroll
;             for (int b = 0; b < 2; ++b)
; #pragma unroll
;                 for (int m = 0; m < 4; ++m)
; #pragma unroll
;                     for (int n = 0; n < 2; ++n) acc[a][b][m][n] = (f32x4){0.f, 0.f, 0.f, 0.f};
.LBB0_662:
	s_ashr_i32 s15, s14, 31
	s_lshl_b64 s[16:17], s[14:15], 19
	s_add_u32 s16, s33, s16
	s_addc_u32 s17, s34, s17
	s_and_b64 s[18:19], s[8:9], exec
	s_cselect_b32 s15, s17, s27
	s_cselect_b32 s21, s16, s26
	s_ashr_i32 s13, s12, 31
	s_lshl_b64 s[18:19], s[12:13], 19
	s_add_u32 s18, s35, s18
	s_addc_u32 s19, s36, s19
	s_and_b64 s[28:29], s[8:9], exec
	s_cselect_b32 s13, s19, s25
	s_cselect_b32 s23, s18, s24
	s_add_u32 s48, s24, 0x100
	s_addc_u32 s49, s25, 0
	s_add_u32 s24, s26, 0x40080
	v_mov_b64_e32 v[2:3], 0
	v_mov_b64_e32 v[4:5], 0
	v_mov_b64_e32 v[6:7], 0
	v_mov_b64_e32 v[8:9], 0
	v_mov_b64_e32 v[10:11], 0
	v_mov_b64_e32 v[12:13], 0
	v_mov_b64_e32 v[14:15], 0
	v_mov_b64_e32 v[16:17], 0
	v_mov_b64_e32 v[18:19], 0
	v_mov_b64_e32 v[20:21], 0
	v_mov_b64_e32 v[22:23], 0
	v_mov_b64_e32 v[24:25], 0
	v_mov_b64_e32 v[26:27], 0
	v_mov_b64_e32 v[28:29], 0
	v_mov_b64_e32 v[30:31], 0
	v_mov_b64_e32 v[32:33], 0
	v_mov_b64_e32 v[34:35], 0
	v_mov_b64_e32 v[36:37], 0
	v_mov_b64_e32 v[38:39], 0
	v_mov_b64_e32 v[40:41], 0
	v_mov_b64_e32 v[42:43], 0
	v_mov_b64_e32 v[44:45], 0
	v_mov_b64_e32 v[46:47], 0
	v_mov_b64_e32 v[48:49], 0
	v_mov_b64_e32 v[50:51], 0
	v_mov_b64_e32 v[52:53], 0
	v_mov_b64_e32 v[54:55], 0
	v_mov_b64_e32 v[56:57], 0
	v_mov_b64_e32 v[58:59], 0
	v_mov_b64_e32 v[60:61], 0
	v_mov_b64_e32 v[62:63], 0
	v_mov_b64_e32 v[64:65], 0
	v_mov_b64_e32 v[66:67], 0
	v_mov_b64_e32 v[68:69], 0
	v_mov_b64_e32 v[70:71], 0
	v_mov_b64_e32 v[72:73], 0
	v_mov_b64_e32 v[74:75], 0
	v_mov_b64_e32 v[76:77], 0
	v_mov_b64_e32 v[78:79], 0
	v_mov_b64_e32 v[80:81], 0
	v_mov_b64_e32 v[82:83], 0
	v_mov_b64_e32 v[84:85], 0
	v_mov_b64_e32 v[86:87], 0
	v_mov_b64_e32 v[88:89], 0
	v_mov_b64_e32 v[90:91], 0
	v_mov_b64_e32 v[92:93], 0
	v_mov_b64_e32 v[94:95], 0
	v_mov_b64_e32 v[96:97], 0
	v_mov_b64_e32 v[98:99], 0
	v_mov_b64_e32 v[100:101], 0
	v_mov_b64_e32 v[102:103], 0
	v_mov_b64_e32 v[104:105], 0
	v_mov_b64_e32 v[106:107], 0
	v_mov_b64_e32 v[108:109], 0
	v_mov_b64_e32 v[110:111], 0
	v_mov_b64_e32 v[112:113], 0
	v_mov_b64_e32 v[114:115], 0
	v_mov_b64_e32 v[116:117], 0
	v_mov_b64_e32 v[118:119], 0
	v_mov_b64_e32 v[120:121], 0
	v_mov_b64_e32 v[122:123], 0
	v_mov_b64_e32 v[124:125], 0
	v_mov_b64_e32 v[126:127], 0
	v_mov_b64_e32 v[128:129], 0
	s_addc_u32 s25, s27, 0
	s_mov_b32 s50, -2
	s_waitcnt lgkmcnt(0)
	s_mov_b64 s[56:57], 0x80

;     __device__ bool next(int i, Unit& u) const { const int j = i / 3, br = i - 3 * j; const int pmn = c + j * G; if (pmn >= 512) return false; u.pm = pmn >> 2; u.pn = br * 4 + (pmn & 3); return true; }
;     __device__ bool next(int i, Unit& u) const { const int j = i / 3, br = i - 3 * j; const int pmn = c + j * G; if (pmn >= 512) return false; u.pm = br * 128 + (pmn >> 2); u.pn = br * 4 + (pmn & 3); return true; }
; template <class Epi, class Sched, bool ALIGN_EPI = false, bool SP2 = false>
; __device__ __forceinline__ void gemm_phase(PG8_LAS unsigned char* lds, const Gemm g, const Sched& S, const Epi& E) {
;     ...
;         const bool has_next = S.next(ui + 1, nxt);
;         const char* nA = has_next ? (const char*)g.A + (size_t)nxt.pm * tstep : cA; const char* nB = has_next ? (const char*)g.Bt + (size_t)nxt.pn * tstep : cB;
;         for (int t = 0; t < nt; t += 2) {
;             const bool last = (t == nt - 2);
;             const char* a1 = cA + (size_t)(t + 1) * kstep;
;             const char* a2 = last ? nA : cA + (size_t)(t + 2) * kstep; const char* b2 = last ? nB : cB + (size_t)(t + 2) * kstep;
;     ...
;         for (int a = 0; a < 2; ++a)
; #pragma unroll
;             for (int b = 0; b < 2; ++b)
; #pragma unroll
;                 for (int m = 0; m < 4; ++m)
; #pragma unroll
;                     for (int n = 0; n < 2; ++n) acc[a][b][m][n] = (f32x4){0.f, 0.f, 0.f, 0.f};
.LBB0_751:
	s_ashr_i32 s13, s12, 31
	s_lshl_b64 s[14:15], s[12:13], 19
	s_add_u32 s14, s28, s14
	s_addc_u32 s15, s29, s15
	s_and_b64 s[16:17], s[6:7], exec
	s_cselect_b32 s13, s15, s23
	s_cselect_b32 s43, s14, s22
	s_ashr_i32 s11, s10, 31
	s_lshl_b64 s[16:17], s[10:11], 19
	s_add_u32 s16, s30, s16
	s_addc_u32 s17, s31, s17
	s_and_b64 s[24:25], s[6:7], exec
	s_cselect_b32 s11, s17, s21
	s_cselect_b32 s44, s16, s20
	s_add_u32 s45, s20, 0x100
	s_addc_u32 s46, s21, 0
	s_add_u32 s20, s22, 0x40080
	v_mov_b64_e32 v[2:3], 0
	v_mov_b64_e32 v[4:5], 0
	v_mov_b64_e32 v[6:7], 0
	v_mov_b64_e32 v[8:9], 0
	v_mov_b64_e32 v[10:11], 0
	v_mov_b64_e32 v[12:13], 0
	v_mov_b64_e32 v[14:15], 0
	v_mov_b64_e32 v[16:17], 0
	v_mov_b64_e32 v[18:19], 0
	v_mov_b64_e32 v[20:21], 0
	v_mov_b64_e32 v[22:23], 0
	v_mov_b64_e32 v[24:25], 0
	v_mov_b64_e32 v[26:27], 0
	v_mov_b64_e32 v[28:29], 0
	v_mov_b64_e32 v[30:31], 0
	v_mov_b64_e32 v[32:33], 0
	v_mov_b64_e32 v[34:35], 0
	v_mov_b64_e32 v[36:37], 0
	v_mov_b64_e32 v[38:39], 0
	v_mov_b64_e32 v[40:41], 0
	v_mov_b64_e32 v[42:43], 0
	v_mov_b64_e32 v[44:45], 0
	v_mov_b64_e32 v[46:47], 0
	v_mov_b64_e32 v[48:49], 0
	v_mov_b64_e32 v[50:51], 0
	v_mov_b64_e32 v[52:53], 0
	v_mov_b64_e32 v[54:55], 0
	v_mov_b64_e32 v[56:57], 0
	v_mov_b64_e32 v[58:59], 0
	v_mov_b64_e32 v[60:61], 0
	v_mov_b64_e32 v[62:63], 0
	v_mov_b64_e32 v[64:65], 0
	v_mov_b64_e32 v[66:67], 0
	v_mov_b64_e32 v[68:69], 0
	v_mov_b64_e32 v[70:71], 0
	v_mov_b64_e32 v[72:73], 0
	v_mov_b64_e32 v[74:75], 0
	v_mov_b64_e32 v[76:77], 0
	v_mov_b64_e32 v[78:79], 0
	v_mov_b64_e32 v[80:81], 0
	v_mov_b64_e32 v[82:83], 0
	v_mov_b64_e32 v[84:85], 0
	v_mov_b64_e32 v[86:87], 0
	v_mov_b64_e32 v[88:89], 0
	v_mov_b64_e32 v[90:91], 0
	v_mov_b64_e32 v[92:93], 0
	v_mov_b64_e32 v[94:95], 0
	v_mov_b64_e32 v[96:97], 0
	v_mov_b64_e32 v[98:99], 0
	v_mov_b64_e32 v[100:101], 0
	v_mov_b64_e32 v[102:103], 0
	v_mov_b64_e32 v[104:105], 0
	v_mov_b64_e32 v[106:107], 0
	v_mov_b64_e32 v[108:109], 0
	v_mov_b64_e32 v[110:111], 0
	v_mov_b64_e32 v[112:113], 0
	v_mov_b64_e32 v[114:115], 0
	v_mov_b64_e32 v[116:117], 0
	v_mov_b64_e32 v[118:119], 0
	v_mov_b64_e32 v[120:121], 0
	v_mov_b64_e32 v[122:123], 0
	v_mov_b64_e32 v[124:125], 0
	v_mov_b64_e32 v[126:127], 0
	v_mov_b64_e32 v[128:129], 0
	s_addc_u32 s21, s23, 0
	s_mov_b32 s47, -2
	s_mov_b64 s[52:53], 0x80

;     __device__ bool next(int i, Unit& u) const { const int j = i / 3, br = i - 3 * j; const int pmn = c + j * G; if (pmn >= 512) return false; u.pm = pmn >> 2; u.pn = br * 4 + (pmn & 3); return true; }
;     __device__ bool next(int i, Unit& u) const { const int j = i / 3, br = i - 3 * j; const int pmn = c + j * G; if (pmn >= 512) return false; u.pm = br * 128 + (pmn >> 2); u.pn = br * 4 + (pmn & 3); return true; }
; template <class Epi, class Sched, bool ALIGN_EPI = false, bool SP2 = false>
; __device__ __forceinline__ void gemm_phase(PG8_LAS unsigned char* lds, const Gemm g, const Sched& S, const Epi& E) {
;     ...
;         const bool has_next = S.next(ui + 1, nxt);
;         const char* nA = has_next ? (const char*)g.A + (size_t)nxt.pm * tstep : cA; const char* nB = has_next ? (const char*)g.Bt + (size_t)nxt.pn * tstep : cB;
;         for (int t = 0; t < nt; t += 2) {
;             const bool last = (t == nt - 2);
;             const char* a1 = cA + (size_t)(t + 1) * kstep;
;             const char* a2 = last ? nA : cA + (size_t)(t + 2) * kstep; const char* b2 = last ? nB : cB + (size_t)(t + 2) * kstep;
;     ...
;         for (int a = 0; a < 2; ++a)
; #pragma unroll
;             for (int b = 0; b < 2; ++b)
; #pragma unroll
;                 for (int m = 0; m < 4; ++m)
; #pragma unroll
;                     for (int n = 0; n < 2; ++n) acc[a][b][m][n] = (f32x4){0.f, 0.f, 0.f, 0.f};
.LBB0_838:
	s_add_u32 s50, s22, 0x100
	v_mov_b64_e32 v[2:3], 0
	v_mov_b64_e32 v[4:5], 0
	v_mov_b64_e32 v[6:7], 0
	v_mov_b64_e32 v[8:9], 0
	v_mov_b64_e32 v[10:11], 0
	v_mov_b64_e32 v[12:13], 0
	v_mov_b64_e32 v[14:15], 0
	v_mov_b64_e32 v[16:17], 0
	v_mov_b64_e32 v[18:19], 0
	v_mov_b64_e32 v[20:21], 0
	v_mov_b64_e32 v[22:23], 0
	v_mov_b64_e32 v[24:25], 0
	v_mov_b64_e32 v[26:27], 0
	v_mov_b64_e32 v[28:29], 0
	v_mov_b64_e32 v[30:31], 0
	v_mov_b64_e32 v[32:33], 0
	v_mov_b64_e32 v[34:35], 0
	v_mov_b64_e32 v[36:37], 0
	v_mov_b64_e32 v[38:39], 0
	v_mov_b64_e32 v[40:41], 0
	v_mov_b64_e32 v[42:43], 0
	v_mov_b64_e32 v[44:45], 0
	v_mov_b64_e32 v[46:47], 0
	v_mov_b64_e32 v[48:49], 0
	v_mov_b64_e32 v[50:51], 0
	v_mov_b64_e32 v[52:53], 0
	v_mov_b64_e32 v[54:55], 0
	v_mov_b64_e32 v[56:57], 0
	v_mov_b64_e32 v[58:59], 0
	v_mov_b64_e32 v[60:61], 0
	v_mov_b64_e32 v[62:63], 0
	v_mov_b64_e32 v[64:65], 0
	v_mov_b64_e32 v[66:67], 0
	v_mov_b64_e32 v[68:69], 0
	v_mov_b64_e32 v[70:71], 0
	v_mov_b64_e32 v[72:73], 0
	v_mov_b64_e32 v[74:75], 0
	v_mov_b64_e32 v[76:77], 0
	v_mov_b64_e32 v[78:79], 0
	v_mov_b64_e32 v[80:81], 0
	v_mov_b64_e32 v[82:83], 0
	v_mov_b64_e32 v[84:85], 0
	v_mov_b64_e32 v[86:87], 0
	v_mov_b64_e32 v[88:89], 0
	v_mov_b64_e32 v[90:91], 0
	v_mov_b64_e32 v[92:93], 0
	v_mov_b64_e32 v[94:95], 0
	v_mov_b64_e32 v[96:97], 0
	v_mov_b64_e32 v[98:99], 0
	v_mov_b64_e32 v[100:101], 0
	v_mov_b64_e32 v[102:103], 0
	v_mov_b64_e32 v[104:105], 0
	v_mov_b64_e32 v[106:107], 0
	v_mov_b64_e32 v[108:109], 0
	v_mov_b64_e32 v[110:111], 0
	v_mov_b64_e32 v[112:113], 0
	v_mov_b64_e32 v[114:115], 0
	v_mov_b64_e32 v[116:117], 0
	v_mov_b64_e32 v[118:119], 0
	v_mov_b64_e32 v[120:121], 0
	v_mov_b64_e32 v[122:123], 0
	v_mov_b64_e32 v[124:125], 0
	v_mov_b64_e32 v[126:127], 0
	v_mov_b64_e32 v[128:129], 0
	s_addc_u32 s51, s23, 0
	s_mov_b32 s52, -2
	s_waitcnt lgkmcnt(0)
	s_mov_b64 s[56:57], 0x80
